# v7 + peeled first K-iteration with C=0 first-touch MFMAs (no accumulator zeroing) + relaxed vmcnt(16) in first two super-phases of FFN-in units
# speedup vs baseline: 1.0069x; 1.0069x over previous
; #define PG8_STAGE(bufoff, gbase, voff) do { _Pragma("unroll") for (int _i = 0; _i < 2; ++_i) \
;         __builtin_amdgcn_global_load_lds((const unsigned*)((const char*)(gbase) + (voff)[_i]), (PG8_LAS unsigned*)(lds + (bufoff) + ldsw + _i * 8192), 16, 0, 0); } while (0)
; #define PG8_WAIT_V(n) asm volatile("s_waitcnt vmcnt(" #n ")" ::: "memory")
; #define PG8_BAR __builtin_amdgcn_s_barrier()
; template <class Epi, class Sched, bool ALIGN_EPI = false, bool SP2 = false>
; __device__ __forceinline__ void gemm_phase(PG8_LAS unsigned char* lds, const Gemm g, const Sched& S, const Epi& E) {
;     ...
;     const int aoff = lds_byte(wr * 64 + fr, fq * 8), boff = lds_byte(wc * 32 + fr, fq * 8);
;     ...
;     Unit cur, nxt; int ui = 0;
;     if (!S.next(0, cur)) return;
;     f32x4 acc[2][2][4][2];
; #pragma unroll
;     for (int a = 0; a < 2; ++a)
; #pragma unroll
;         for (int b = 0; b < 2; ++b)
; #pragma unroll
;             for (int m = 0; m < 4; ++m)
; #pragma unroll
;                 for (int n = 0; n < 2; ++n) acc[a][b][m][n] = (f32x4){0.f, 0.f, 0.f, 0.f};
;     bf16x8 At[4][2], B0[2][2], B1[2][2];
;     const char* cA = (const char*)g.A + (size_t)cur.pm * tstep; const char* cB = (const char*)g.Bt + (size_t)cur.pn * tstep;
;     S.a_ready(cur);
;     if constexpr (SP2) {
;         PG8_STAGE(PG8_SB(0, 0), cB, voffB); PG8_STAGE(PG8_SB(0, 1), cB + hstep, voffB); PG8_STAGE(PG8_SA(0, 0), cA, voffA); PG8_STAGE(PG8_SA(0, 1), cA + hstep, voffA);
;         if (wr == 1) PG8_BAR;
;         PG8_WAIT_V(2); PG8_BAR;
;         PG8_STAGE(PG8_SB(1, 0), cB + kstep, voffB); PG8_STAGE(PG8_SA(1, 0), cA + kstep, voffA); PG8_STAGE(PG8_SB(1, 1), cB + hstep + kstep, voffB);
;         PG8_WAIT_V(6); PG8_BAR;
.LBB0_358:
	v_lshl_add_u64 v[10:11], s[18:19], 0, v[0:1]
	v_mov_b32_e32 v131, v1
	v_readlane_b32 s16, v254, 2
	s_lshl_b32 s6, s6, 5
	v_lshl_add_u64 v[12:13], s[18:19], 0, v[130:131]
	v_mov_b32_e32 v135, v1
	v_readlane_b32 s17, v254, 3
	s_and_b32 s9, s6, 0x60
	s_add_i32 m0, s25, 0x18000
	v_lshl_add_u64 v[10:11], v[10:11], 0, s[38:39]
	v_lshl_add_u64 v[14:15], s[16:17], 0, v[134:135]
	v_mov_b32_e32 v133, v1
	s_lshl_b32 s8, s5, 13
	s_lshl_b32 s10, s9, 7
	s_waitcnt vmcnt(2)
	s_barrier
	global_load_lds_dwordx4 v[10:11], off
	v_lshl_add_u64 v[10:11], v[12:13], 0, s[38:39]
	s_add_i32 m0, s25, 0x1a000
	s_add_i32 s29, s25, 0x8000
	s_add_i32 s30, s25, 0xa000
	v_lshl_add_u64 v[16:17], s[16:17], 0, v[132:133]
	global_load_lds_dwordx4 v[10:11], off
	v_lshl_add_u64 v[10:11], v[14:15], 0, s[38:39]
	s_mov_b32 m0, s29
	s_add_u32 s6, s18, 0x40080
	global_load_lds_dwordx4 v[10:11], off
	v_lshl_add_u64 v[10:11], v[16:17], 0, s[38:39]
	s_mov_b32 m0, s30
	s_addc_u32 s7, s19, 0
	global_load_lds_dwordx4 v[10:11], off
	s_add_i32 m0, s25, 0x1c000
	v_lshl_add_u64 v[10:11], s[6:7], 0, v[0:1]
	global_load_lds_dwordx4 v[10:11], off
	v_lshl_add_u64 v[10:11], s[6:7], 0, v[130:131]
	s_add_i32 m0, s25, 0x1e000
	v_and_b32_e32 v9, 15, v2
	global_load_lds_dwordx4 v[10:11], off
	v_lshrrev_b32_e32 v10, 1, v2
	v_and_b32_e32 v10, 24, v10
	v_lshlrev_b32_e32 v11, 1, v10
	v_lshlrev_b32_e32 v2, 2, v2
	v_lshl_or_b32 v142, s5, 6, v9
	v_lshl_or_b32 v9, v9, 6, v11
	v_and_b32_e32 v2, 32, v2
	v_bitop3_b32 v11, v9, s8, v2 bitop3:0xde
	v_bitop3_b32 v143, v9, s10, v2 bitop3:0xde
	v_lshlrev_b32_e32 v2, 14, v7
	v_and_b32_e32 v2, 0xffff8000, v2
	v_lshl_add_u32 v2, v6, 11, v2
	v_and_b32_e32 v6, 1, v7
	v_lshl_or_b32 v2, v6, 6, v2
	v_lshl_add_u32 v136, v8, 1, v2
	v_lshlrev_b32_e32 v2, 14, v3
	v_and_b32_e32 v2, 0xffff8000, v2
	s_waitcnt vmcnt(6)
	v_lshl_add_u32 v2, v4, 11, v2
	v_and_b32_e32 v3, 1, v3
	s_cmpk_lt_u32 s4, 0x100
	v_lshl_or_b32 v2, v3, 6, v2
	v_readlane_b32 s4, v254, 0
	s_cselect_b64 s[6:7], -1, 0
	v_or_b32_e32 v144, s9, v10
	v_mov_b32_e32 v137, v1
	v_lshl_add_u32 v138, v5, 1, v2
	v_mov_b32_e32 v139, v1
	s_mov_b32 s31, 0
	v_add_u32_e32 v145, 0, v11
	v_readlane_b32 s33, v253, 61
	s_mov_b32 s49, s4
	s_barrier
	v_readlane_b32 s5, v254, 1
	s_waitcnt vmcnt(0)
	s_branch .LBB0_361

; #define PG8_STAGE(bufoff, gbase, voff) do { _Pragma("unroll") for (int _i = 0; _i < 2; ++_i) \
;         __builtin_amdgcn_global_load_lds((const unsigned*)((const char*)(gbase) + (voff)[_i]), (PG8_LAS unsigned*)(lds + (bufoff) + ldsw + _i * 8192), 16, 0, 0); } while (0)
; #define PG8_LDA(dst, b, h) do { _Pragma("unroll") for (int m = 0; m < 4; ++m) _Pragma("unroll") for (int k = 0; k < 2; ++k) dst[m][k] = *(const PG8_LAS bf16x8*)(lds + PG8_SA(b, h) + aoff + m * 2048 + k * 1024); } while (0)
; #define PG8_LDB(dst, b, h) do { _Pragma("unroll") for (int n = 0; n < 2; ++n) _Pragma("unroll") for (int k = 0; k < 2; ++k) dst[n][k] = *(const PG8_LAS bf16x8*)(lds + PG8_SB(b, h) + boff + n * 2048 + k * 1024); } while (0)
; #define PG8_MMA(ai, bj, At, Bt) do { __builtin_amdgcn_s_setprio(1); _Pragma("unroll") for (int m = 0; m < 4; ++m) _Pragma("unroll") for (int n = 0; n < 2; ++n) _Pragma("unroll") for (int k = 0; k < 2; ++k) \
;         acc[ai][bj][m][n] = __builtin_amdgcn_mfma_f32_16x16x32_bf16(Bt[n][k], At[m][k], acc[ai][bj][m][n], 0, 0, 0); __builtin_amdgcn_s_setprio(0); } while (0)
; #define PG8_BAR __builtin_amdgcn_s_barrier()
; template <class Epi, class Sched, bool ALIGN_EPI = false, bool SP2 = false>
; __device__ __forceinline__ void gemm_phase(PG8_LAS unsigned char* lds, const Gemm g, const Sched& S, const Epi& E) {
;     ...
;         const bool has_next = S.next(ui + 1, nxt);
;         const char* nA = has_next ? (const char*)g.A + (size_t)nxt.pm * tstep : cA; const char* nB = has_next ? (const char*)g.Bt + (size_t)nxt.pn * tstep : cB;
;         for (int t = 0; t < nt; t += 2) {
;             const bool last = (t == nt - 2);
;             const char* a1 = cA + (size_t)(t + 1) * kstep;
;             const char* a2 = last ? nA : cA + (size_t)(t + 2) * kstep; const char* b2 = last ? nB : cB + (size_t)(t + 2) * kstep;
;             const char* a3 = a2 + kstep; const char* b3 = b2 + kstep;
;             if (last && has_next) S.a_ready(nxt);
;             if constexpr (SP2) {
;             PG8_LDB(B0, 0, 0); PG8_LDB(B1, 0, 1); PG8_SCHED; PG8_LDA(At, 0, 0); PG8_STAGE(PG8_SA(1, 1), a1 + hstep, voffA);
;             PG8_WAIT_V(8); PG8_WAIT_L(0); PG8_BAR; PG8_MMA(0, 0, At, B0); PG8_MMA(0, 1, At, B1); PG8_BAR; PG8_SCHED;
;             PG8_LDA(At, 0, 1); PG8_STAGE(PG8_SB(0, 0), b2, voffB); PG8_STAGE(PG8_SB(0, 1), b2 + hstep, voffB); PG8_STAGE(PG8_SA(0, 0), a2, voffA);
.LBB0_367:
	s_ashr_i32 s11, s10, 31
	s_lshl_b64 s[12:13], s[10:11], 19
	s_add_u32 s12, s90, s12
	s_addc_u32 s13, s91, s13
	s_and_b64 s[14:15], s[4:5], exec
	s_cselect_b32 s11, s13, s17
	s_cselect_b32 s50, s12, s16
	s_ashr_i32 s9, s8, 31
	s_lshl_b64 s[14:15], s[8:9], 19
	s_add_u32 s14, s22, s14
	s_addc_u32 s15, s23, s15
	s_and_b64 s[20:21], s[4:5], exec
	s_cselect_b32 s9, s15, s19
	s_cselect_b32 s51, s14, s18
	s_add_u32 s16, s16, 0x40080
	s_addc_u32 s17, s17, 0
	s_add_u32 s52, s18, 0x100
	s_addc_u32 s53, s19, 0
	s_mov_b32 s55, -2
	s_add_u32 s18, s16, 0xfffc0080
	s_addc_u32 s19, s17, -1
	s_add_i32 s56, 0, 0x10000
	s_cmp_eq_u32 s55, 12
	s_cselect_b32 s21, s11, s19
	s_cselect_b32 s20, s50, s18
	v_add_u32_e32 v140, s56, v143
	s_cselect_b32 s19, s9, s53
	s_cselect_b32 s18, s51, s52
	s_add_i32 s58, 0, 0x14000
	ds_read_b128 v[154:157], v140
	ds_read_b128 v[158:161], v140 offset:1024
	ds_read_b128 v[162:165], v140 offset:2048
	ds_read_b128 v[166:169], v140 offset:3072
	v_add_u32_e32 v140, s58, v143
	ds_read_b128 v[170:173], v140
	ds_read_b128 v[174:177], v140 offset:1024
	ds_read_b128 v[178:181], v140 offset:2048
	ds_read_b128 v[200:203], v140 offset:3072
	v_lshl_add_u64 v[140:141], s[16:17], 0, v[136:137]
	s_add_i32 m0, s25, 0xc000
	ds_read_b128 v[204:207], v145
	ds_read_b128 v[208:211], v145 offset:1024
	ds_read_b128 v[212:215], v145 offset:2048
	ds_read_b128 v[216:219], v145 offset:3072
	ds_read_b128 v[220:223], v145 offset:4096
	ds_read_b128 v[224:227], v145 offset:5120
	ds_read_b128 v[228:231], v145 offset:6144
	ds_read_b128 v[232:235], v145 offset:7168
	global_load_lds_dwordx4 v[140:141], off
	v_lshl_add_u64 v[140:141], s[16:17], 0, v[138:139]
	s_add_i32 m0, s25, 0xe000
	s_nop 0
	global_load_lds_dwordx4 v[140:141], off
	s_waitcnt vmcnt(16)
	s_waitcnt lgkmcnt(0)
	s_barrier
	s_setprio 1
	s_waitcnt lgkmcnt(0)
	v_mfma_f32_16x16x32_bf16 v[122:125], v[154:157], v[204:207], 0
	v_mfma_f32_16x16x32_bf16 v[114:117], v[162:165], v[204:207], 0
	v_mfma_f32_16x16x32_bf16 v[106:109], v[154:157], v[212:215], 0
	v_mfma_f32_16x16x32_bf16 v[98:101], v[162:165], v[212:215], 0
	v_mfma_f32_16x16x32_bf16 v[90:93], v[154:157], v[220:223], 0
	v_mfma_f32_16x16x32_bf16 v[82:85], v[162:165], v[220:223], 0
	v_mfma_f32_16x16x32_bf16 v[74:77], v[154:157], v[228:231], 0
	v_mfma_f32_16x16x32_bf16 v[66:69], v[162:165], v[228:231], 0
	v_mfma_f32_16x16x32_bf16 v[122:125], v[158:161], v[208:211], v[122:125]
	v_mfma_f32_16x16x32_bf16 v[114:117], v[166:169], v[208:211], v[114:117]
	v_mfma_f32_16x16x32_bf16 v[106:109], v[158:161], v[216:219], v[106:109]
	v_mfma_f32_16x16x32_bf16 v[98:101], v[166:169], v[216:219], v[98:101]
	v_mfma_f32_16x16x32_bf16 v[90:93], v[158:161], v[224:227], v[90:93]
	v_mfma_f32_16x16x32_bf16 v[82:85], v[166:169], v[224:227], v[82:85]
	v_mfma_f32_16x16x32_bf16 v[74:77], v[158:161], v[232:235], v[74:77]
	v_mfma_f32_16x16x32_bf16 v[66:69], v[166:169], v[232:235], v[66:69]
	s_setprio 0
	s_setprio 1
	v_mfma_f32_16x16x32_bf16 v[126:129], v[170:173], v[204:207], 0
	v_mfma_f32_16x16x32_bf16 v[118:121], v[178:181], v[204:207], 0
	v_mfma_f32_16x16x32_bf16 v[110:113], v[170:173], v[212:215], 0
	v_mfma_f32_16x16x32_bf16 v[102:105], v[178:181], v[212:215], 0
	v_mfma_f32_16x16x32_bf16 v[94:97], v[170:173], v[220:223], 0
	v_mfma_f32_16x16x32_bf16 v[86:89], v[178:181], v[220:223], 0
	v_mfma_f32_16x16x32_bf16 v[78:81], v[170:173], v[228:231], 0
	v_mfma_f32_16x16x32_bf16 v[70:73], v[178:181], v[228:231], 0
	v_mfma_f32_16x16x32_bf16 v[126:129], v[174:177], v[208:211], v[126:129]
	v_mfma_f32_16x16x32_bf16 v[118:121], v[200:203], v[208:211], v[118:121]
	v_mfma_f32_16x16x32_bf16 v[110:113], v[174:177], v[216:219], v[110:113]
	v_mfma_f32_16x16x32_bf16 v[102:105], v[200:203], v[216:219], v[102:105]
	v_mfma_f32_16x16x32_bf16 v[94:97], v[174:177], v[224:227], v[94:97]
	v_mfma_f32_16x16x32_bf16 v[86:89], v[200:203], v[224:227], v[86:89]
	v_mfma_f32_16x16x32_bf16 v[78:81], v[174:177], v[232:235], v[78:81]
	v_mfma_f32_16x16x32_bf16 v[70:73], v[200:203], v[232:235], v[70:73]
	s_setprio 0
	s_barrier
	s_add_i32 s56, s56, s24
	v_lshl_add_u64 v[140:141], s[18:19], 0, v[0:1]
	s_mov_b32 m0, s56
	ds_read_b128 v[204:207], v145 offset:16384
	ds_read_b128 v[208:211], v145 offset:17408
	ds_read_b128 v[212:215], v145 offset:18432
	ds_read_b128 v[216:219], v145 offset:19456
	ds_read_b128 v[220:223], v145 offset:20480
	ds_read_b128 v[224:227], v145 offset:21504
	ds_read_b128 v[228:231], v145 offset:22528
	ds_read_b128 v[232:235], v145 offset:23552
	global_load_lds_dwordx4 v[140:141], off
	s_add_i32 m0, s56, 0x2000
	s_add_u32 s56, s18, 0x40000
	v_lshl_add_u64 v[146:147], s[18:19], 0, v[130:131]
	s_addc_u32 s57, s19, 0
	s_add_i32 s58, s58, s24
	global_load_lds_dwordx4 v[146:147], off
	v_lshl_add_u64 v[148:149], s[56:57], 0, v[0:1]
	s_mov_b32 m0, s58
	v_lshl_add_u64 v[236:237], s[20:21], 0, v[132:133]
	global_load_lds_dwordx4 v[148:149], off
	v_lshl_add_u64 v[148:149], s[56:57], 0, v[130:131]
	s_add_i32 m0, s58, 0x2000
	s_nop 0
	global_load_lds_dwordx4 v[148:149], off
	v_lshl_add_u64 v[148:149], s[20:21], 0, v[134:135]
	s_mov_b32 m0, s25
	s_nop 0
	global_load_lds_dwordx4 v[148:149], off
	s_mov_b32 m0, s26
	s_nop 0
	global_load_lds_dwordx4 v[236:237], off
	s_waitcnt vmcnt(16)
	s_waitcnt lgkmcnt(0)
	s_barrier
; #define PG8_STAGE(bufoff, gbase, voff) do { _Pragma("unroll") for (int _i = 0; _i < 2; ++_i) \
;         __builtin_amdgcn_global_load_lds((const unsigned*)((const char*)(gbase) + (voff)[_i]), (PG8_LAS unsigned*)(lds + (bufoff) + ldsw + _i * 8192), 16, 0, 0); } while (0)
; #define PG8_LDA(dst, b, h) do { _Pragma("unroll") for (int m = 0; m < 4; ++m) _Pragma("unroll") for (int k = 0; k < 2; ++k) dst[m][k] = *(const PG8_LAS bf16x8*)(lds + PG8_SA(b, h) + aoff + m * 2048 + k * 1024); } while (0)
; #define PG8_LDB(dst, b, h) do { _Pragma("unroll") for (int n = 0; n < 2; ++n) _Pragma("unroll") for (int k = 0; k < 2; ++k) dst[n][k] = *(const PG8_LAS bf16x8*)(lds + PG8_SB(b, h) + boff + n * 2048 + k * 1024); } while (0)
; #define PG8_MMA(ai, bj, At, Bt) do { __builtin_amdgcn_s_setprio(1); _Pragma("unroll") for (int m = 0; m < 4; ++m) _Pragma("unroll") for (int n = 0; n < 2; ++n) _Pragma("unroll") for (int k = 0; k < 2; ++k) \
;         acc[ai][bj][m][n] = __builtin_amdgcn_mfma_f32_16x16x32_bf16(Bt[n][k], At[m][k], acc[ai][bj][m][n], 0, 0, 0); __builtin_amdgcn_s_setprio(0); } while (0)
; #define PG8_WAIT_V(n) asm volatile("s_waitcnt vmcnt(" #n ")" ::: "memory")
; #define PG8_WAIT_L(n) asm volatile("s_waitcnt lgkmcnt(" #n ")" ::: "memory")
; #define PG8_BAR __builtin_amdgcn_s_barrier()
; #define PG8_SCHED __builtin_amdgcn_sched_barrier(0)
; template <class Epi, class Sched, bool ALIGN_EPI = false, bool SP2 = false>
; __device__ __forceinline__ void gemm_phase(PG8_LAS unsigned char* lds, const Gemm g, const Sched& S, const Epi& E) {
;     ...
;             PG8_WAIT_V(8); PG8_WAIT_L(0); PG8_BAR; PG8_MMA(1, 0, At, B0); PG8_MMA(1, 1, At, B1); PG8_BAR; PG8_SCHED;
;             PG8_LDB(B0, 1, 0); PG8_LDB(B1, 1, 1); PG8_SCHED; PG8_LDA(At, 1, 0); PG8_STAGE(PG8_SA(0, 1), a2 + hstep, voffA);
;             PG8_WAIT_V(8); PG8_WAIT_L(0); PG8_BAR; PG8_MMA(0, 0, At, B0); PG8_MMA(0, 1, At, B1); PG8_BAR; PG8_SCHED;
;             PG8_LDA(At, 1, 1); PG8_STAGE(PG8_SB(1, 0), b3, voffB); PG8_STAGE(PG8_SB(1, 1), b3 + hstep, voffB); PG8_STAGE(PG8_SA(1, 0), a3, voffA);
	s_setprio 1
	s_waitcnt lgkmcnt(0)
	v_mfma_f32_16x16x32_bf16 v[58:61], v[154:157], v[204:207], 0
	v_mfma_f32_16x16x32_bf16 v[50:53], v[162:165], v[204:207], 0
	v_mfma_f32_16x16x32_bf16 v[42:45], v[154:157], v[212:215], 0
	v_mfma_f32_16x16x32_bf16 v[34:37], v[162:165], v[212:215], 0
	v_mfma_f32_16x16x32_bf16 v[26:29], v[154:157], v[220:223], 0
	v_mfma_f32_16x16x32_bf16 v[18:21], v[162:165], v[220:223], 0
	v_mfma_f32_16x16x32_bf16 v[10:13], v[154:157], v[228:231], 0
	v_mfma_f32_16x16x32_bf16 v[2:5], v[162:165], v[228:231], 0
	v_mfma_f32_16x16x32_bf16 v[58:61], v[158:161], v[208:211], v[58:61]
	v_mfma_f32_16x16x32_bf16 v[50:53], v[166:169], v[208:211], v[50:53]
	v_mfma_f32_16x16x32_bf16 v[42:45], v[158:161], v[216:219], v[42:45]
	v_mfma_f32_16x16x32_bf16 v[34:37], v[166:169], v[216:219], v[34:37]
	v_mfma_f32_16x16x32_bf16 v[26:29], v[158:161], v[224:227], v[26:29]
	v_mfma_f32_16x16x32_bf16 v[18:21], v[166:169], v[224:227], v[18:21]
	v_mfma_f32_16x16x32_bf16 v[10:13], v[158:161], v[232:235], v[10:13]
	v_mfma_f32_16x16x32_bf16 v[2:5], v[166:169], v[232:235], v[2:5]
	s_setprio 0
	s_setprio 1
	v_mfma_f32_16x16x32_bf16 v[62:65], v[170:173], v[204:207], 0
	v_mfma_f32_16x16x32_bf16 v[54:57], v[178:181], v[204:207], 0
	v_mfma_f32_16x16x32_bf16 v[46:49], v[170:173], v[212:215], 0
	v_mfma_f32_16x16x32_bf16 v[38:41], v[178:181], v[212:215], 0
	v_mfma_f32_16x16x32_bf16 v[30:33], v[170:173], v[220:223], 0
	v_mfma_f32_16x16x32_bf16 v[22:25], v[178:181], v[220:223], 0
	v_mfma_f32_16x16x32_bf16 v[14:17], v[170:173], v[228:231], 0
	v_mfma_f32_16x16x32_bf16 v[6:9], v[178:181], v[228:231], 0
	v_mfma_f32_16x16x32_bf16 v[62:65], v[174:177], v[208:211], v[62:65]
	v_mfma_f32_16x16x32_bf16 v[54:57], v[200:203], v[208:211], v[54:57]
	v_mfma_f32_16x16x32_bf16 v[46:49], v[174:177], v[216:219], v[46:49]
	v_mfma_f32_16x16x32_bf16 v[38:41], v[200:203], v[216:219], v[38:41]
	v_mfma_f32_16x16x32_bf16 v[30:33], v[174:177], v[224:227], v[30:33]
	v_mfma_f32_16x16x32_bf16 v[22:25], v[200:203], v[224:227], v[22:25]
	v_mfma_f32_16x16x32_bf16 v[14:17], v[174:177], v[232:235], v[14:17]
	v_mfma_f32_16x16x32_bf16 v[6:9], v[200:203], v[232:235], v[6:9]
	s_setprio 0
	s_barrier
	s_add_i32 s56, 0, 0x18000
	s_add_i32 s57, 0, 0x1c000
	v_add_u32_e32 v166, s56, v143
	v_add_u32_e32 v200, s57, v143
	ds_read_b128 v[154:157], v166
	ds_read_b128 v[158:161], v166 offset:1024
	ds_read_b128 v[162:165], v166 offset:2048
	ds_read_b128 v[166:169], v166 offset:3072
	ds_read_b128 v[170:173], v200
	ds_read_b128 v[174:177], v200 offset:1024
	ds_read_b128 v[178:181], v200 offset:2048
	ds_read_b128 v[200:203], v200 offset:3072
	s_add_u32 s20, s20, 0x40000
	s_addc_u32 s21, s21, 0
	s_mov_b32 m0, s27
	v_lshl_add_u64 v[238:239], s[20:21], 0, v[134:135]
	ds_read_b128 v[204:207], v145 offset:32768
	ds_read_b128 v[208:211], v145 offset:33792
	ds_read_b128 v[212:215], v145 offset:34816
	ds_read_b128 v[216:219], v145 offset:35840
	ds_read_b128 v[220:223], v145 offset:36864
	ds_read_b128 v[224:227], v145 offset:37888
	ds_read_b128 v[228:231], v145 offset:38912
	ds_read_b128 v[232:235], v145 offset:39936
	global_load_lds_dwordx4 v[238:239], off
	v_lshl_add_u64 v[238:239], s[20:21], 0, v[132:133]
	s_mov_b32 m0, s28
	s_nop 0
	global_load_lds_dwordx4 v[238:239], off
	s_waitcnt vmcnt(8)
	s_waitcnt lgkmcnt(0)
	s_barrier
	s_setprio 1
	s_waitcnt lgkmcnt(0)
	v_mfma_f32_16x16x32_bf16 v[122:125], v[154:157], v[204:207], v[122:125]
	v_mfma_f32_16x16x32_bf16 v[114:117], v[162:165], v[204:207], v[114:117]
	v_mfma_f32_16x16x32_bf16 v[106:109], v[154:157], v[212:215], v[106:109]
	v_mfma_f32_16x16x32_bf16 v[98:101], v[162:165], v[212:215], v[98:101]
	v_mfma_f32_16x16x32_bf16 v[90:93], v[154:157], v[220:223], v[90:93]
	v_mfma_f32_16x16x32_bf16 v[82:85], v[162:165], v[220:223], v[82:85]
	v_mfma_f32_16x16x32_bf16 v[74:77], v[154:157], v[228:231], v[74:77]
	v_mfma_f32_16x16x32_bf16 v[66:69], v[162:165], v[228:231], v[66:69]
	v_mfma_f32_16x16x32_bf16 v[122:125], v[158:161], v[208:211], v[122:125]
	v_mfma_f32_16x16x32_bf16 v[114:117], v[166:169], v[208:211], v[114:117]
	v_mfma_f32_16x16x32_bf16 v[106:109], v[158:161], v[216:219], v[106:109]
	v_mfma_f32_16x16x32_bf16 v[98:101], v[166:169], v[216:219], v[98:101]
	v_mfma_f32_16x16x32_bf16 v[90:93], v[158:161], v[224:227], v[90:93]
	v_mfma_f32_16x16x32_bf16 v[82:85], v[166:169], v[224:227], v[82:85]
	v_mfma_f32_16x16x32_bf16 v[74:77], v[158:161], v[232:235], v[74:77]
	v_mfma_f32_16x16x32_bf16 v[66:69], v[166:169], v[232:235], v[66:69]
	s_setprio 0
	s_setprio 1
	v_mfma_f32_16x16x32_bf16 v[126:129], v[170:173], v[204:207], v[126:129]
	v_mfma_f32_16x16x32_bf16 v[118:121], v[178:181], v[204:207], v[118:121]
	v_mfma_f32_16x16x32_bf16 v[110:113], v[170:173], v[212:215], v[110:113]
	v_mfma_f32_16x16x32_bf16 v[102:105], v[178:181], v[212:215], v[102:105]
	v_mfma_f32_16x16x32_bf16 v[94:97], v[170:173], v[220:223], v[94:97]
	v_mfma_f32_16x16x32_bf16 v[86:89], v[178:181], v[220:223], v[86:89]
	v_mfma_f32_16x16x32_bf16 v[78:81], v[170:173], v[228:231], v[78:81]
	v_mfma_f32_16x16x32_bf16 v[70:73], v[178:181], v[228:231], v[70:73]
	v_mfma_f32_16x16x32_bf16 v[126:129], v[174:177], v[208:211], v[126:129]
	v_mfma_f32_16x16x32_bf16 v[118:121], v[200:203], v[208:211], v[118:121]
	v_mfma_f32_16x16x32_bf16 v[110:113], v[174:177], v[216:219], v[110:113]
	v_mfma_f32_16x16x32_bf16 v[102:105], v[200:203], v[216:219], v[102:105]
	v_mfma_f32_16x16x32_bf16 v[94:97], v[174:177], v[224:227], v[94:97]
	v_mfma_f32_16x16x32_bf16 v[86:89], v[200:203], v[224:227], v[86:89]
	v_mfma_f32_16x16x32_bf16 v[78:81], v[174:177], v[232:235], v[78:81]
	v_mfma_f32_16x16x32_bf16 v[70:73], v[200:203], v[232:235], v[70:73]
	s_setprio 0
	s_barrier
; #define PG8_STAGE(bufoff, gbase, voff) do { _Pragma("unroll") for (int _i = 0; _i < 2; ++_i) \
;         __builtin_amdgcn_global_load_lds((const unsigned*)((const char*)(gbase) + (voff)[_i]), (PG8_LAS unsigned*)(lds + (bufoff) + ldsw + _i * 8192), 16, 0, 0); } while (0)
; #define PG8_LDA(dst, b, h) do { _Pragma("unroll") for (int m = 0; m < 4; ++m) _Pragma("unroll") for (int k = 0; k < 2; ++k) dst[m][k] = *(const PG8_LAS bf16x8*)(lds + PG8_SA(b, h) + aoff + m * 2048 + k * 1024); } while (0)
; #define PG8_MMA(ai, bj, At, Bt) do { __builtin_amdgcn_s_setprio(1); _Pragma("unroll") for (int m = 0; m < 4; ++m) _Pragma("unroll") for (int n = 0; n < 2; ++n) _Pragma("unroll") for (int k = 0; k < 2; ++k) \
;         acc[ai][bj][m][n] = __builtin_amdgcn_mfma_f32_16x16x32_bf16(Bt[n][k], At[m][k], acc[ai][bj][m][n], 0, 0, 0); __builtin_amdgcn_s_setprio(0); } while (0)
; #define PG8_WAIT_V(n) asm volatile("s_waitcnt vmcnt(" #n ")" ::: "memory")
; #define PG8_WAIT_L(n) asm volatile("s_waitcnt lgkmcnt(" #n ")" ::: "memory")
; #define PG8_BAR __builtin_amdgcn_s_barrier()
; #define PG8_SCHED __builtin_amdgcn_sched_barrier(0)
; template <class Epi, class Sched, bool ALIGN_EPI = false, bool SP2 = false>
; __device__ __forceinline__ void gemm_phase(PG8_LAS unsigned char* lds, const Gemm g, const Sched& S, const Epi& E) {
;     ...
;         for (int t = 0; t < nt; t += 2) {
;             const bool last = (t == nt - 2);
;             const char* a1 = cA + (size_t)(t + 1) * kstep;
;             const char* a2 = last ? nA : cA + (size_t)(t + 2) * kstep; const char* b2 = last ? nB : cB + (size_t)(t + 2) * kstep;
;             const char* a3 = a2 + kstep; const char* b3 = b2 + kstep;
;     ...
;             PG8_LDA(At, 1, 1); PG8_STAGE(PG8_SB(1, 0), b3, voffB); PG8_STAGE(PG8_SB(1, 1), b3 + hstep, voffB); PG8_STAGE(PG8_SA(1, 0), a3, voffA);
;             PG8_WAIT_V(8); PG8_WAIT_L(0); PG8_BAR; PG8_MMA(1, 0, At, B0); PG8_MMA(1, 1, At, B1); PG8_BAR; PG8_SCHED;
	s_add_i32 s20, s56, s24
	v_lshl_add_u64 v[140:141], v[140:141], 0, s[38:39]
	s_mov_b32 m0, s20
	ds_read_b128 v[204:207], v145 offset:49152
	ds_read_b128 v[208:211], v145 offset:50176
	ds_read_b128 v[212:215], v145 offset:51200
	ds_read_b128 v[216:219], v145 offset:52224
	ds_read_b128 v[220:223], v145 offset:53248
	ds_read_b128 v[224:227], v145 offset:54272
	ds_read_b128 v[228:231], v145 offset:55296
	ds_read_b128 v[232:235], v145 offset:56320
	global_load_lds_dwordx4 v[140:141], off
	s_add_i32 m0, s20, 0x2000
	s_add_u32 s18, s18, 0x40080
	v_lshl_add_u64 v[140:141], v[146:147], 0, s[38:39]
	s_addc_u32 s19, s19, 0
	s_add_i32 s20, s57, s24
	global_load_lds_dwordx4 v[140:141], off
	v_lshl_add_u64 v[140:141], s[18:19], 0, v[0:1]
	s_mov_b32 m0, s20
	s_nop 0
	global_load_lds_dwordx4 v[140:141], off
	v_lshl_add_u64 v[140:141], s[18:19], 0, v[130:131]
	s_add_i32 m0, s20, 0x2000
	s_nop 0
	global_load_lds_dwordx4 v[140:141], off
	v_lshl_add_u64 v[140:141], v[148:149], 0, s[38:39]
	s_mov_b32 m0, s29
	s_nop 0
	global_load_lds_dwordx4 v[140:141], off
	v_lshl_add_u64 v[140:141], v[236:237], 0, s[38:39]
	s_mov_b32 m0, s30
	s_nop 0
	global_load_lds_dwordx4 v[140:141], off
	s_waitcnt vmcnt(8)
	s_waitcnt lgkmcnt(0)
	s_barrier
	s_setprio 1
	s_waitcnt lgkmcnt(0)
	v_mfma_f32_16x16x32_bf16 v[58:61], v[154:157], v[204:207], v[58:61]
	v_mfma_f32_16x16x32_bf16 v[50:53], v[162:165], v[204:207], v[50:53]
	v_mfma_f32_16x16x32_bf16 v[42:45], v[154:157], v[212:215], v[42:45]
	v_mfma_f32_16x16x32_bf16 v[34:37], v[162:165], v[212:215], v[34:37]
	v_mfma_f32_16x16x32_bf16 v[26:29], v[154:157], v[220:223], v[26:29]
	v_mfma_f32_16x16x32_bf16 v[18:21], v[162:165], v[220:223], v[18:21]
	v_mfma_f32_16x16x32_bf16 v[10:13], v[154:157], v[228:231], v[10:13]
	v_mfma_f32_16x16x32_bf16 v[2:5], v[162:165], v[228:231], v[2:5]
	v_mfma_f32_16x16x32_bf16 v[58:61], v[158:161], v[208:211], v[58:61]
	v_mfma_f32_16x16x32_bf16 v[50:53], v[166:169], v[208:211], v[50:53]
	v_mfma_f32_16x16x32_bf16 v[42:45], v[158:161], v[216:219], v[42:45]
	v_mfma_f32_16x16x32_bf16 v[34:37], v[166:169], v[216:219], v[34:37]
	v_mfma_f32_16x16x32_bf16 v[26:29], v[158:161], v[224:227], v[26:29]
	v_mfma_f32_16x16x32_bf16 v[18:21], v[166:169], v[224:227], v[18:21]
	v_mfma_f32_16x16x32_bf16 v[10:13], v[158:161], v[232:235], v[10:13]
	v_mfma_f32_16x16x32_bf16 v[2:5], v[166:169], v[232:235], v[2:5]
	s_setprio 0
	s_setprio 1
	v_mfma_f32_16x16x32_bf16 v[62:65], v[170:173], v[204:207], v[62:65]
	v_mfma_f32_16x16x32_bf16 v[54:57], v[178:181], v[204:207], v[54:57]
	v_mfma_f32_16x16x32_bf16 v[46:49], v[170:173], v[212:215], v[46:49]
	v_mfma_f32_16x16x32_bf16 v[38:41], v[178:181], v[212:215], v[38:41]
	v_mfma_f32_16x16x32_bf16 v[30:33], v[170:173], v[220:223], v[30:33]
	v_mfma_f32_16x16x32_bf16 v[22:25], v[178:181], v[220:223], v[22:25]
	v_mfma_f32_16x16x32_bf16 v[14:17], v[170:173], v[228:231], v[14:17]
	v_mfma_f32_16x16x32_bf16 v[6:9], v[178:181], v[228:231], v[6:9]
	v_mfma_f32_16x16x32_bf16 v[62:65], v[174:177], v[208:211], v[62:65]
	v_mfma_f32_16x16x32_bf16 v[54:57], v[200:203], v[208:211], v[54:57]
	v_mfma_f32_16x16x32_bf16 v[46:49], v[174:177], v[216:219], v[46:49]
	v_mfma_f32_16x16x32_bf16 v[38:41], v[200:203], v[216:219], v[38:41]
	v_mfma_f32_16x16x32_bf16 v[30:33], v[174:177], v[224:227], v[30:33]
	v_mfma_f32_16x16x32_bf16 v[22:25], v[200:203], v[224:227], v[22:25]
	v_mfma_f32_16x16x32_bf16 v[14:17], v[174:177], v[232:235], v[14:17]
	v_mfma_f32_16x16x32_bf16 v[6:9], v[200:203], v[232:235], v[6:9]
	s_setprio 0
	s_barrier
	s_add_i32 s55, s55, 2
	s_add_u32 s16, s16, 0x100
	s_addc_u32 s17, s17, 0
	s_add_u32 s52, s52, 0x100
	s_addc_u32 s53, s53, 0

; #define PG8_STAGE(bufoff, gbase, voff) do { _Pragma("unroll") for (int _i = 0; _i < 2; ++_i) \
;         __builtin_amdgcn_global_load_lds((const unsigned*)((const char*)(gbase) + (voff)[_i]), (PG8_LAS unsigned*)(lds + (bufoff) + ldsw + _i * 8192), 16, 0, 0); } while (0)
; #define PG8_LDA(dst, b, h) do { _Pragma("unroll") for (int m = 0; m < 4; ++m) _Pragma("unroll") for (int k = 0; k < 2; ++k) dst[m][k] = *(const PG8_LAS bf16x8*)(lds + PG8_SA(b, h) + aoff + m * 2048 + k * 1024); } while (0)
; #define PG8_LDB(dst, b, h) do { _Pragma("unroll") for (int n = 0; n < 2; ++n) _Pragma("unroll") for (int k = 0; k < 2; ++k) dst[n][k] = *(const PG8_LAS bf16x8*)(lds + PG8_SB(b, h) + boff + n * 2048 + k * 1024); } while (0)
; #define PG8_MMA(ai, bj, At, Bt) do { __builtin_amdgcn_s_setprio(1); _Pragma("unroll") for (int m = 0; m < 4; ++m) _Pragma("unroll") for (int n = 0; n < 2; ++n) _Pragma("unroll") for (int k = 0; k < 2; ++k) \
;         acc[ai][bj][m][n] = __builtin_amdgcn_mfma_f32_16x16x32_bf16(Bt[n][k], At[m][k], acc[ai][bj][m][n], 0, 0, 0); __builtin_amdgcn_s_setprio(0); } while (0)
; #define PG8_BAR __builtin_amdgcn_s_barrier()
; template <class Epi, class Sched, bool ALIGN_EPI = false, bool SP2 = false>
; __device__ __forceinline__ void gemm_phase(PG8_LAS unsigned char* lds, const Gemm g, const Sched& S, const Epi& E) {
;     ...
;         const bool has_next = S.next(ui + 1, nxt);
;         const char* nA = has_next ? (const char*)g.A + (size_t)nxt.pm * tstep : cA; const char* nB = has_next ? (const char*)g.Bt + (size_t)nxt.pn * tstep : cB;
;         for (int t = 0; t < nt; t += 2) {
;             const bool last = (t == nt - 2);
;             const char* a1 = cA + (size_t)(t + 1) * kstep;
;             const char* a2 = last ? nA : cA + (size_t)(t + 2) * kstep; const char* b2 = last ? nB : cB + (size_t)(t + 2) * kstep;
;             const char* a3 = a2 + kstep; const char* b3 = b2 + kstep;
;             if (last && has_next) S.a_ready(nxt);
;             if constexpr (SP2) {
;             PG8_LDB(B0, 0, 0); PG8_LDB(B1, 0, 1); PG8_SCHED; PG8_LDA(At, 0, 0); PG8_STAGE(PG8_SA(1, 1), a1 + hstep, voffA);
;             PG8_WAIT_V(8); PG8_WAIT_L(0); PG8_BAR; PG8_MMA(0, 0, At, B0); PG8_MMA(0, 1, At, B1); PG8_BAR; PG8_SCHED;
;             PG8_LDA(At, 0, 1); PG8_STAGE(PG8_SB(0, 0), b2, voffB); PG8_STAGE(PG8_SB(0, 1), b2 + hstep, voffB); PG8_STAGE(PG8_SA(0, 0), a2, voffA);
.LBB0_431:
	s_ashr_i32 s11, s10, 31
	s_lshl_b64 s[12:13], s[10:11], 21
	s_add_u32 s12, s92, s12
	s_addc_u32 s13, s93, s13
	s_and_b64 s[14:15], s[4:5], exec
	s_cselect_b32 s11, s13, s17
	s_cselect_b32 s51, s12, s16
	s_ashr_i32 s9, s8, 31
	s_lshl_b64 s[14:15], s[8:9], 21
	s_add_u32 s14, s22, s14
	s_addc_u32 s15, s23, s15
	s_and_b64 s[20:21], s[4:5], exec
	s_cselect_b32 s9, s15, s19
	s_cselect_b32 s52, s14, s18
	s_add_u32 s16, s16, 0x100080
	s_addc_u32 s17, s17, 0
	s_add_u32 s53, s18, 0x100
	s_addc_u32 s54, s19, 0
	s_mov_b32 s55, -2
	s_add_u32 s18, s16, 0xfff00080
	s_addc_u32 s19, s17, -1
	s_add_i32 s56, 0, 0x10000
	s_cmp_eq_u32 s55, 60
	s_cselect_b32 s21, s11, s19
	s_cselect_b32 s20, s51, s18
	s_cselect_b32 s19, s9, s54
	s_cselect_b32 s18, s52, s53
	s_add_i32 s58, 0, 0x14000
	v_add_u32_e32 v142, s56, v201
	v_add_u32_e32 v146, s58, v201
	ds_read_b128 v[130:133], v142
	ds_read_b128 v[134:137], v142 offset:1024
	ds_read_b128 v[138:141], v142 offset:2048
	ds_read_b128 v[142:145], v142 offset:3072
	ds_read_b128 v[164:167], v146
	ds_read_b128 v[168:171], v146 offset:1024
	ds_read_b128 v[172:175], v146 offset:2048
	ds_read_b128 v[176:179], v146 offset:3072
	v_lshl_add_u64 v[146:147], s[16:17], 0, v[160:161]
	s_add_i32 m0, s25, 0xc000
	ds_read_b128 v[204:207], v203
	ds_read_b128 v[208:211], v203 offset:1024
	ds_read_b128 v[212:215], v203 offset:2048
	ds_read_b128 v[216:219], v203 offset:3072
	ds_read_b128 v[220:223], v203 offset:4096
	ds_read_b128 v[224:227], v203 offset:5120
	ds_read_b128 v[228:231], v203 offset:6144
	ds_read_b128 v[232:235], v203 offset:7168
	global_load_lds_dwordx4 v[146:147], off
	v_lshl_add_u64 v[146:147], s[16:17], 0, v[162:163]
	s_add_i32 m0, s25, 0xe000
	s_nop 0
	global_load_lds_dwordx4 v[146:147], off
	s_waitcnt vmcnt(8)
	s_waitcnt lgkmcnt(0)
	s_barrier
	s_setprio 1
	s_waitcnt lgkmcnt(0)
	v_mfma_f32_16x16x32_bf16 v[126:129], v[130:133], v[204:207], 0
	v_mfma_f32_16x16x32_bf16 v[122:125], v[138:141], v[204:207], 0
	v_mfma_f32_16x16x32_bf16 v[118:121], v[130:133], v[212:215], 0
	v_mfma_f32_16x16x32_bf16 v[114:117], v[138:141], v[212:215], 0
	v_mfma_f32_16x16x32_bf16 v[110:113], v[130:133], v[220:223], 0
	v_mfma_f32_16x16x32_bf16 v[106:109], v[138:141], v[220:223], 0
	v_mfma_f32_16x16x32_bf16 v[102:105], v[130:133], v[228:231], 0
	v_mfma_f32_16x16x32_bf16 v[98:101], v[138:141], v[228:231], 0
	v_mfma_f32_16x16x32_bf16 v[126:129], v[134:137], v[208:211], v[126:129]
	v_mfma_f32_16x16x32_bf16 v[122:125], v[142:145], v[208:211], v[122:125]
	v_mfma_f32_16x16x32_bf16 v[118:121], v[134:137], v[216:219], v[118:121]
	v_mfma_f32_16x16x32_bf16 v[114:117], v[142:145], v[216:219], v[114:117]
	v_mfma_f32_16x16x32_bf16 v[110:113], v[134:137], v[224:227], v[110:113]
	v_mfma_f32_16x16x32_bf16 v[106:109], v[142:145], v[224:227], v[106:109]
	v_mfma_f32_16x16x32_bf16 v[102:105], v[134:137], v[232:235], v[102:105]
	v_mfma_f32_16x16x32_bf16 v[98:101], v[142:145], v[232:235], v[98:101]
	s_setprio 0
	s_setprio 1
	v_mfma_f32_16x16x32_bf16 v[62:65], v[164:167], v[204:207], 0
	v_mfma_f32_16x16x32_bf16 v[58:61], v[172:175], v[204:207], 0
	v_mfma_f32_16x16x32_bf16 v[54:57], v[164:167], v[212:215], 0
	v_mfma_f32_16x16x32_bf16 v[50:53], v[172:175], v[212:215], 0
	v_mfma_f32_16x16x32_bf16 v[46:49], v[164:167], v[220:223], 0
	v_mfma_f32_16x16x32_bf16 v[42:45], v[172:175], v[220:223], 0
	v_mfma_f32_16x16x32_bf16 v[38:41], v[164:167], v[228:231], 0
	v_mfma_f32_16x16x32_bf16 v[34:37], v[172:175], v[228:231], 0
	v_mfma_f32_16x16x32_bf16 v[62:65], v[168:171], v[208:211], v[62:65]
	v_mfma_f32_16x16x32_bf16 v[58:61], v[176:179], v[208:211], v[58:61]
	v_mfma_f32_16x16x32_bf16 v[54:57], v[168:171], v[216:219], v[54:57]
	v_mfma_f32_16x16x32_bf16 v[50:53], v[176:179], v[216:219], v[50:53]
	v_mfma_f32_16x16x32_bf16 v[46:49], v[168:171], v[224:227], v[46:49]
	v_mfma_f32_16x16x32_bf16 v[42:45], v[176:179], v[224:227], v[42:45]
	v_mfma_f32_16x16x32_bf16 v[38:41], v[168:171], v[232:235], v[38:41]
	v_mfma_f32_16x16x32_bf16 v[34:37], v[176:179], v[232:235], v[34:37]
	s_setprio 0
	s_barrier
	s_add_i32 s56, s56, s24
	v_lshl_add_u64 v[146:147], s[18:19], 0, v[0:1]
	s_mov_b32 m0, s56
	ds_read_b128 v[204:207], v203 offset:16384
	ds_read_b128 v[208:211], v203 offset:17408
	ds_read_b128 v[212:215], v203 offset:18432
	ds_read_b128 v[216:219], v203 offset:19456
	ds_read_b128 v[220:223], v203 offset:20480
	ds_read_b128 v[224:227], v203 offset:21504
	ds_read_b128 v[228:231], v203 offset:22528
	ds_read_b128 v[232:235], v203 offset:23552
	global_load_lds_dwordx4 v[146:147], off
	s_add_i32 m0, s56, 0x2000
	s_add_u32 s56, s18, 0x100000
	v_lshl_add_u64 v[148:149], s[18:19], 0, v[154:155]
	s_addc_u32 s57, s19, 0
	s_add_i32 s58, s58, s24
	global_load_lds_dwordx4 v[148:149], off
	v_lshl_add_u64 v[180:181], s[56:57], 0, v[0:1]
	s_mov_b32 m0, s58
	v_lshl_add_u64 v[236:237], s[20:21], 0, v[156:157]
	global_load_lds_dwordx4 v[180:181], off
	v_lshl_add_u64 v[180:181], s[56:57], 0, v[154:155]
	s_add_i32 m0, s58, 0x2000
	s_nop 0
	global_load_lds_dwordx4 v[180:181], off
	v_lshl_add_u64 v[180:181], s[20:21], 0, v[158:159]
	s_mov_b32 m0, s25
	s_nop 0
	global_load_lds_dwordx4 v[180:181], off
	s_mov_b32 m0, s26
	s_nop 0
	global_load_lds_dwordx4 v[236:237], off
	s_waitcnt vmcnt(8)
	s_waitcnt lgkmcnt(0)
	s_barrier
; #define PG8_STAGE(bufoff, gbase, voff) do { _Pragma("unroll") for (int _i = 0; _i < 2; ++_i) \
;         __builtin_amdgcn_global_load_lds((const unsigned*)((const char*)(gbase) + (voff)[_i]), (PG8_LAS unsigned*)(lds + (bufoff) + ldsw + _i * 8192), 16, 0, 0); } while (0)
; #define PG8_LDA(dst, b, h) do { _Pragma("unroll") for (int m = 0; m < 4; ++m) _Pragma("unroll") for (int k = 0; k < 2; ++k) dst[m][k] = *(const PG8_LAS bf16x8*)(lds + PG8_SA(b, h) + aoff + m * 2048 + k * 1024); } while (0)
; #define PG8_LDB(dst, b, h) do { _Pragma("unroll") for (int n = 0; n < 2; ++n) _Pragma("unroll") for (int k = 0; k < 2; ++k) dst[n][k] = *(const PG8_LAS bf16x8*)(lds + PG8_SB(b, h) + boff + n * 2048 + k * 1024); } while (0)
; #define PG8_MMA(ai, bj, At, Bt) do { __builtin_amdgcn_s_setprio(1); _Pragma("unroll") for (int m = 0; m < 4; ++m) _Pragma("unroll") for (int n = 0; n < 2; ++n) _Pragma("unroll") for (int k = 0; k < 2; ++k) \
;         acc[ai][bj][m][n] = __builtin_amdgcn_mfma_f32_16x16x32_bf16(Bt[n][k], At[m][k], acc[ai][bj][m][n], 0, 0, 0); __builtin_amdgcn_s_setprio(0); } while (0)
; #define PG8_WAIT_V(n) asm volatile("s_waitcnt vmcnt(" #n ")" ::: "memory")
; #define PG8_WAIT_L(n) asm volatile("s_waitcnt lgkmcnt(" #n ")" ::: "memory")
; #define PG8_BAR __builtin_amdgcn_s_barrier()
; #define PG8_SCHED __builtin_amdgcn_sched_barrier(0)
; template <class Epi, class Sched, bool ALIGN_EPI = false, bool SP2 = false>
; __device__ __forceinline__ void gemm_phase(PG8_LAS unsigned char* lds, const Gemm g, const Sched& S, const Epi& E) {
;     ...
;             PG8_WAIT_V(8); PG8_WAIT_L(0); PG8_BAR; PG8_MMA(1, 0, At, B0); PG8_MMA(1, 1, At, B1); PG8_BAR; PG8_SCHED;
;             PG8_LDB(B0, 1, 0); PG8_LDB(B1, 1, 1); PG8_SCHED; PG8_LDA(At, 1, 0); PG8_STAGE(PG8_SA(0, 1), a2 + hstep, voffA);
;             PG8_WAIT_V(8); PG8_WAIT_L(0); PG8_BAR; PG8_MMA(0, 0, At, B0); PG8_MMA(0, 1, At, B1); PG8_BAR; PG8_SCHED;
;             PG8_LDA(At, 1, 1); PG8_STAGE(PG8_SB(1, 0), b3, voffB); PG8_STAGE(PG8_SB(1, 1), b3 + hstep, voffB); PG8_STAGE(PG8_SA(1, 0), a3, voffA);
	s_setprio 1
	s_waitcnt lgkmcnt(0)
	v_mfma_f32_16x16x32_bf16 v[94:97], v[130:133], v[204:207], 0
	v_mfma_f32_16x16x32_bf16 v[90:93], v[138:141], v[204:207], 0
	v_mfma_f32_16x16x32_bf16 v[86:89], v[130:133], v[212:215], 0
	v_mfma_f32_16x16x32_bf16 v[82:85], v[138:141], v[212:215], 0
	v_mfma_f32_16x16x32_bf16 v[78:81], v[130:133], v[220:223], 0
	v_mfma_f32_16x16x32_bf16 v[74:77], v[138:141], v[220:223], 0
	v_mfma_f32_16x16x32_bf16 v[70:73], v[130:133], v[228:231], 0
	v_mfma_f32_16x16x32_bf16 v[66:69], v[138:141], v[228:231], 0
	v_mfma_f32_16x16x32_bf16 v[94:97], v[134:137], v[208:211], v[94:97]
	v_mfma_f32_16x16x32_bf16 v[90:93], v[142:145], v[208:211], v[90:93]
	v_mfma_f32_16x16x32_bf16 v[86:89], v[134:137], v[216:219], v[86:89]
	v_mfma_f32_16x16x32_bf16 v[82:85], v[142:145], v[216:219], v[82:85]
	v_mfma_f32_16x16x32_bf16 v[78:81], v[134:137], v[224:227], v[78:81]
	v_mfma_f32_16x16x32_bf16 v[74:77], v[142:145], v[224:227], v[74:77]
	v_mfma_f32_16x16x32_bf16 v[70:73], v[134:137], v[232:235], v[70:73]
	v_mfma_f32_16x16x32_bf16 v[66:69], v[142:145], v[232:235], v[66:69]
	s_setprio 0
	s_setprio 1
	v_mfma_f32_16x16x32_bf16 v[30:33], v[164:167], v[204:207], 0
	v_mfma_f32_16x16x32_bf16 v[26:29], v[172:175], v[204:207], 0
	v_mfma_f32_16x16x32_bf16 v[22:25], v[164:167], v[212:215], 0
	v_mfma_f32_16x16x32_bf16 v[18:21], v[172:175], v[212:215], 0
	v_mfma_f32_16x16x32_bf16 v[14:17], v[164:167], v[220:223], 0
	v_mfma_f32_16x16x32_bf16 v[10:13], v[172:175], v[220:223], 0
	v_mfma_f32_16x16x32_bf16 v[6:9], v[164:167], v[228:231], 0
	v_mfma_f32_16x16x32_bf16 v[2:5], v[172:175], v[228:231], 0
	v_mfma_f32_16x16x32_bf16 v[30:33], v[168:171], v[208:211], v[30:33]
	v_mfma_f32_16x16x32_bf16 v[26:29], v[176:179], v[208:211], v[26:29]
	v_mfma_f32_16x16x32_bf16 v[22:25], v[168:171], v[216:219], v[22:25]
	v_mfma_f32_16x16x32_bf16 v[18:21], v[176:179], v[216:219], v[18:21]
	v_mfma_f32_16x16x32_bf16 v[14:17], v[168:171], v[224:227], v[14:17]
	v_mfma_f32_16x16x32_bf16 v[10:13], v[176:179], v[224:227], v[10:13]
	v_mfma_f32_16x16x32_bf16 v[6:9], v[168:171], v[232:235], v[6:9]
	v_mfma_f32_16x16x32_bf16 v[2:5], v[176:179], v[232:235], v[2:5]
	s_setprio 0
	s_barrier
	s_add_i32 s56, 0, 0x18000
	s_add_i32 s57, 0, 0x1c000
	v_add_u32_e32 v142, s56, v201
	v_add_u32_e32 v176, s57, v201
	ds_read_b128 v[130:133], v142
	ds_read_b128 v[134:137], v142 offset:1024
	ds_read_b128 v[138:141], v142 offset:2048
	ds_read_b128 v[142:145], v142 offset:3072
	ds_read_b128 v[164:167], v176
	ds_read_b128 v[168:171], v176 offset:1024
	ds_read_b128 v[172:175], v176 offset:2048
	ds_read_b128 v[176:179], v176 offset:3072
	s_add_u32 s20, s20, 0x100000
	s_addc_u32 s21, s21, 0
	s_mov_b32 m0, s27
	v_lshl_add_u64 v[238:239], s[20:21], 0, v[158:159]
	ds_read_b128 v[204:207], v203 offset:32768
	ds_read_b128 v[208:211], v203 offset:33792
	ds_read_b128 v[212:215], v203 offset:34816
	ds_read_b128 v[216:219], v203 offset:35840
	ds_read_b128 v[220:223], v203 offset:36864
	ds_read_b128 v[224:227], v203 offset:37888
	ds_read_b128 v[228:231], v203 offset:38912
	ds_read_b128 v[232:235], v203 offset:39936
	global_load_lds_dwordx4 v[238:239], off
	v_lshl_add_u64 v[238:239], s[20:21], 0, v[156:157]
	s_mov_b32 m0, s28
	s_nop 0
	global_load_lds_dwordx4 v[238:239], off
	s_waitcnt vmcnt(8)
	s_waitcnt lgkmcnt(0)
	s_barrier
	s_setprio 1
	s_waitcnt lgkmcnt(0)
	v_mfma_f32_16x16x32_bf16 v[126:129], v[130:133], v[204:207], v[126:129]
	v_mfma_f32_16x16x32_bf16 v[122:125], v[138:141], v[204:207], v[122:125]
	v_mfma_f32_16x16x32_bf16 v[118:121], v[130:133], v[212:215], v[118:121]
	v_mfma_f32_16x16x32_bf16 v[114:117], v[138:141], v[212:215], v[114:117]
	v_mfma_f32_16x16x32_bf16 v[110:113], v[130:133], v[220:223], v[110:113]
	v_mfma_f32_16x16x32_bf16 v[106:109], v[138:141], v[220:223], v[106:109]
	v_mfma_f32_16x16x32_bf16 v[102:105], v[130:133], v[228:231], v[102:105]
	v_mfma_f32_16x16x32_bf16 v[98:101], v[138:141], v[228:231], v[98:101]
	v_mfma_f32_16x16x32_bf16 v[126:129], v[134:137], v[208:211], v[126:129]
	v_mfma_f32_16x16x32_bf16 v[122:125], v[142:145], v[208:211], v[122:125]
	v_mfma_f32_16x16x32_bf16 v[118:121], v[134:137], v[216:219], v[118:121]
	v_mfma_f32_16x16x32_bf16 v[114:117], v[142:145], v[216:219], v[114:117]
	v_mfma_f32_16x16x32_bf16 v[110:113], v[134:137], v[224:227], v[110:113]
	v_mfma_f32_16x16x32_bf16 v[106:109], v[142:145], v[224:227], v[106:109]
	v_mfma_f32_16x16x32_bf16 v[102:105], v[134:137], v[232:235], v[102:105]
	v_mfma_f32_16x16x32_bf16 v[98:101], v[142:145], v[232:235], v[98:101]
	s_setprio 0
	s_setprio 1
	v_mfma_f32_16x16x32_bf16 v[62:65], v[164:167], v[204:207], v[62:65]
	v_mfma_f32_16x16x32_bf16 v[58:61], v[172:175], v[204:207], v[58:61]
	v_mfma_f32_16x16x32_bf16 v[54:57], v[164:167], v[212:215], v[54:57]
	v_mfma_f32_16x16x32_bf16 v[50:53], v[172:175], v[212:215], v[50:53]
	v_mfma_f32_16x16x32_bf16 v[46:49], v[164:167], v[220:223], v[46:49]
	v_mfma_f32_16x16x32_bf16 v[42:45], v[172:175], v[220:223], v[42:45]
	v_mfma_f32_16x16x32_bf16 v[38:41], v[164:167], v[228:231], v[38:41]
	v_mfma_f32_16x16x32_bf16 v[34:37], v[172:175], v[228:231], v[34:37]
	v_mfma_f32_16x16x32_bf16 v[62:65], v[168:171], v[208:211], v[62:65]
	v_mfma_f32_16x16x32_bf16 v[58:61], v[176:179], v[208:211], v[58:61]
	v_mfma_f32_16x16x32_bf16 v[54:57], v[168:171], v[216:219], v[54:57]
	v_mfma_f32_16x16x32_bf16 v[50:53], v[176:179], v[216:219], v[50:53]
	v_mfma_f32_16x16x32_bf16 v[46:49], v[168:171], v[224:227], v[46:49]
	v_mfma_f32_16x16x32_bf16 v[42:45], v[176:179], v[224:227], v[42:45]
	v_mfma_f32_16x16x32_bf16 v[38:41], v[168:171], v[232:235], v[38:41]
	v_mfma_f32_16x16x32_bf16 v[34:37], v[176:179], v[232:235], v[34:37]
	s_setprio 0
	s_barrier
; #define PG8_STAGE(bufoff, gbase, voff) do { _Pragma("unroll") for (int _i = 0; _i < 2; ++_i) \
;         __builtin_amdgcn_global_load_lds((const unsigned*)((const char*)(gbase) + (voff)[_i]), (PG8_LAS unsigned*)(lds + (bufoff) + ldsw + _i * 8192), 16, 0, 0); } while (0)
; #define PG8_LDA(dst, b, h) do { _Pragma("unroll") for (int m = 0; m < 4; ++m) _Pragma("unroll") for (int k = 0; k < 2; ++k) dst[m][k] = *(const PG8_LAS bf16x8*)(lds + PG8_SA(b, h) + aoff + m * 2048 + k * 1024); } while (0)
; #define PG8_MMA(ai, bj, At, Bt) do { __builtin_amdgcn_s_setprio(1); _Pragma("unroll") for (int m = 0; m < 4; ++m) _Pragma("unroll") for (int n = 0; n < 2; ++n) _Pragma("unroll") for (int k = 0; k < 2; ++k) \
;         acc[ai][bj][m][n] = __builtin_amdgcn_mfma_f32_16x16x32_bf16(Bt[n][k], At[m][k], acc[ai][bj][m][n], 0, 0, 0); __builtin_amdgcn_s_setprio(0); } while (0)
; #define PG8_WAIT_V(n) asm volatile("s_waitcnt vmcnt(" #n ")" ::: "memory")
; #define PG8_WAIT_L(n) asm volatile("s_waitcnt lgkmcnt(" #n ")" ::: "memory")
; #define PG8_BAR __builtin_amdgcn_s_barrier()
; #define PG8_SCHED __builtin_amdgcn_sched_barrier(0)
; template <class Epi, class Sched, bool ALIGN_EPI = false, bool SP2 = false>
; __device__ __forceinline__ void gemm_phase(PG8_LAS unsigned char* lds, const Gemm g, const Sched& S, const Epi& E) {
;     ...
;         for (int t = 0; t < nt; t += 2) {
;             const bool last = (t == nt - 2);
;             const char* a1 = cA + (size_t)(t + 1) * kstep;
;             const char* a2 = last ? nA : cA + (size_t)(t + 2) * kstep; const char* b2 = last ? nB : cB + (size_t)(t + 2) * kstep;
;             const char* a3 = a2 + kstep; const char* b3 = b2 + kstep;
;     ...
;             PG8_LDA(At, 1, 1); PG8_STAGE(PG8_SB(1, 0), b3, voffB); PG8_STAGE(PG8_SB(1, 1), b3 + hstep, voffB); PG8_STAGE(PG8_SA(1, 0), a3, voffA);
;             PG8_WAIT_V(8); PG8_WAIT_L(0); PG8_BAR; PG8_MMA(1, 0, At, B0); PG8_MMA(1, 1, At, B1); PG8_BAR; PG8_SCHED;
	s_add_i32 s20, s56, s24
	v_lshl_add_u64 v[146:147], v[146:147], 0, s[38:39]
	s_mov_b32 m0, s20
	ds_read_b128 v[204:207], v203 offset:49152
	ds_read_b128 v[208:211], v203 offset:50176
	ds_read_b128 v[212:215], v203 offset:51200
	ds_read_b128 v[216:219], v203 offset:52224
	ds_read_b128 v[220:223], v203 offset:53248
	ds_read_b128 v[224:227], v203 offset:54272
	ds_read_b128 v[228:231], v203 offset:55296
	ds_read_b128 v[232:235], v203 offset:56320
	global_load_lds_dwordx4 v[146:147], off
	s_add_i32 m0, s20, 0x2000
	s_add_u32 s18, s18, 0x100080
	v_lshl_add_u64 v[146:147], v[148:149], 0, s[38:39]
	s_addc_u32 s19, s19, 0
	s_add_i32 s20, s57, s24
	global_load_lds_dwordx4 v[146:147], off
	v_lshl_add_u64 v[146:147], s[18:19], 0, v[0:1]
	s_mov_b32 m0, s20
	s_nop 0
	global_load_lds_dwordx4 v[146:147], off
	v_lshl_add_u64 v[146:147], s[18:19], 0, v[154:155]
	s_add_i32 m0, s20, 0x2000
	s_nop 0
	global_load_lds_dwordx4 v[146:147], off
	v_lshl_add_u64 v[146:147], v[180:181], 0, s[38:39]
	s_mov_b32 m0, s31
	s_nop 0
	global_load_lds_dwordx4 v[146:147], off
	v_lshl_add_u64 v[146:147], v[236:237], 0, s[38:39]
	s_mov_b32 m0, s33
	s_nop 0
	global_load_lds_dwordx4 v[146:147], off
	s_waitcnt vmcnt(8)
	s_waitcnt lgkmcnt(0)
	s_barrier
	s_setprio 1
	s_waitcnt lgkmcnt(0)
	v_mfma_f32_16x16x32_bf16 v[94:97], v[130:133], v[204:207], v[94:97]
	v_mfma_f32_16x16x32_bf16 v[90:93], v[138:141], v[204:207], v[90:93]
	v_mfma_f32_16x16x32_bf16 v[86:89], v[130:133], v[212:215], v[86:89]
	v_mfma_f32_16x16x32_bf16 v[82:85], v[138:141], v[212:215], v[82:85]
	v_mfma_f32_16x16x32_bf16 v[78:81], v[130:133], v[220:223], v[78:81]
	v_mfma_f32_16x16x32_bf16 v[74:77], v[138:141], v[220:223], v[74:77]
	v_mfma_f32_16x16x32_bf16 v[70:73], v[130:133], v[228:231], v[70:73]
	v_mfma_f32_16x16x32_bf16 v[66:69], v[138:141], v[228:231], v[66:69]
	v_mfma_f32_16x16x32_bf16 v[94:97], v[134:137], v[208:211], v[94:97]
	v_mfma_f32_16x16x32_bf16 v[90:93], v[142:145], v[208:211], v[90:93]
	v_mfma_f32_16x16x32_bf16 v[86:89], v[134:137], v[216:219], v[86:89]
	v_mfma_f32_16x16x32_bf16 v[82:85], v[142:145], v[216:219], v[82:85]
	v_mfma_f32_16x16x32_bf16 v[78:81], v[134:137], v[224:227], v[78:81]
	v_mfma_f32_16x16x32_bf16 v[74:77], v[142:145], v[224:227], v[74:77]
	v_mfma_f32_16x16x32_bf16 v[70:73], v[134:137], v[232:235], v[70:73]
	v_mfma_f32_16x16x32_bf16 v[66:69], v[142:145], v[232:235], v[66:69]
	s_setprio 0
	s_setprio 1
	v_mfma_f32_16x16x32_bf16 v[30:33], v[164:167], v[204:207], v[30:33]
	v_mfma_f32_16x16x32_bf16 v[26:29], v[172:175], v[204:207], v[26:29]
	v_mfma_f32_16x16x32_bf16 v[22:25], v[164:167], v[212:215], v[22:25]
	v_mfma_f32_16x16x32_bf16 v[18:21], v[172:175], v[212:215], v[18:21]
	v_mfma_f32_16x16x32_bf16 v[14:17], v[164:167], v[220:223], v[14:17]
	v_mfma_f32_16x16x32_bf16 v[10:13], v[172:175], v[220:223], v[10:13]
	v_mfma_f32_16x16x32_bf16 v[6:9], v[164:167], v[228:231], v[6:9]
	v_mfma_f32_16x16x32_bf16 v[2:5], v[172:175], v[228:231], v[2:5]
	v_mfma_f32_16x16x32_bf16 v[30:33], v[168:171], v[208:211], v[30:33]
	v_mfma_f32_16x16x32_bf16 v[26:29], v[176:179], v[208:211], v[26:29]
	v_mfma_f32_16x16x32_bf16 v[22:25], v[168:171], v[216:219], v[22:25]
	v_mfma_f32_16x16x32_bf16 v[18:21], v[176:179], v[216:219], v[18:21]
	v_mfma_f32_16x16x32_bf16 v[14:17], v[168:171], v[224:227], v[14:17]
	v_mfma_f32_16x16x32_bf16 v[10:13], v[176:179], v[224:227], v[10:13]
	v_mfma_f32_16x16x32_bf16 v[6:9], v[168:171], v[232:235], v[6:9]
	v_mfma_f32_16x16x32_bf16 v[2:5], v[176:179], v[232:235], v[2:5]
	s_setprio 0
	s_barrier
	s_add_i32 s55, s55, 2
	s_add_u32 s16, s16, 0x100
	s_addc_u32 s17, s17, 0
	s_add_u32 s53, s53, 0x100
	s_addc_u32 s54, s54, 0

; #define PG8_STAGE(bufoff, gbase, voff) do { _Pragma("unroll") for (int _i = 0; _i < 2; ++_i) \
;         __builtin_amdgcn_global_load_lds((const unsigned*)((const char*)(gbase) + (voff)[_i]), (PG8_LAS unsigned*)(lds + (bufoff) + ldsw + _i * 8192), 16, 0, 0); } while (0)
; #define PG8_LDA(dst, b, h) do { _Pragma("unroll") for (int m = 0; m < 4; ++m) _Pragma("unroll") for (int k = 0; k < 2; ++k) dst[m][k] = *(const PG8_LAS bf16x8*)(lds + PG8_SA(b, h) + aoff + m * 2048 + k * 1024); } while (0)
; #define PG8_LDB(dst, b, h) do { _Pragma("unroll") for (int n = 0; n < 2; ++n) _Pragma("unroll") for (int k = 0; k < 2; ++k) dst[n][k] = *(const PG8_LAS bf16x8*)(lds + PG8_SB(b, h) + boff + n * 2048 + k * 1024); } while (0)
; #define PG8_MMA(ai, bj, At, Bt) do { __builtin_amdgcn_s_setprio(1); _Pragma("unroll") for (int m = 0; m < 4; ++m) _Pragma("unroll") for (int n = 0; n < 2; ++n) _Pragma("unroll") for (int k = 0; k < 2; ++k) \
;         acc[ai][bj][m][n] = __builtin_amdgcn_mfma_f32_16x16x32_bf16(Bt[n][k], At[m][k], acc[ai][bj][m][n], 0, 0, 0); __builtin_amdgcn_s_setprio(0); } while (0)
; #define PG8_BAR __builtin_amdgcn_s_barrier()
; template <class Epi, class Sched, bool ALIGN_EPI = false, bool SP2 = false>
; __device__ __forceinline__ void gemm_phase(PG8_LAS unsigned char* lds, const Gemm g, const Sched& S, const Epi& E) {
;     ...
;         const bool has_next = S.next(ui + 1, nxt);
;         const char* nA = has_next ? (const char*)g.A + (size_t)nxt.pm * tstep : cA; const char* nB = has_next ? (const char*)g.Bt + (size_t)nxt.pn * tstep : cB;
;         for (int t = 0; t < nt; t += 2) {
;             const bool last = (t == nt - 2);
;             const char* a1 = cA + (size_t)(t + 1) * kstep;
;             const char* a2 = last ? nA : cA + (size_t)(t + 2) * kstep; const char* b2 = last ? nB : cB + (size_t)(t + 2) * kstep;
;             const char* a3 = a2 + kstep; const char* b3 = b2 + kstep;
;             if (last && has_next) S.a_ready(nxt);
;             if constexpr (SP2) {
;             PG8_LDB(B0, 0, 0); PG8_LDB(B1, 0, 1); PG8_SCHED; PG8_LDA(At, 0, 0); PG8_STAGE(PG8_SA(1, 1), a1 + hstep, voffA);
;             PG8_WAIT_V(8); PG8_WAIT_L(0); PG8_BAR; PG8_MMA(0, 0, At, B0); PG8_MMA(0, 1, At, B1); PG8_BAR; PG8_SCHED;
;             PG8_LDA(At, 0, 1); PG8_STAGE(PG8_SB(0, 0), b2, voffB); PG8_STAGE(PG8_SB(0, 1), b2 + hstep, voffB); PG8_STAGE(PG8_SA(0, 0), a2, voffA);
.LBB0_557:
	s_ashr_i32 s15, s14, 31
	s_lshl_b64 s[16:17], s[14:15], 19
	s_add_u32 s16, s90, s16
	s_addc_u32 s17, s91, s17
	s_and_b64 s[18:19], s[6:7], exec
	s_cselect_b32 s15, s17, s23
	s_cselect_b32 s21, s16, s22
	s_ashr_i32 s13, s12, 31
	s_lshl_b64 s[18:19], s[12:13], 19
	s_add_u32 s18, s28, s18
	s_addc_u32 s19, s29, s19
	s_and_b64 s[26:27], s[6:7], exec
	s_cselect_b32 s13, s19, s25
	s_cselect_b32 s60, s18, s24
	s_add_u32 s22, s22, 0x40080
	s_addc_u32 s23, s23, 0
	s_add_u32 s61, s24, 0x100
	s_addc_u32 s62, s25, 0
	s_mov_b32 s63, -2
	s_waitcnt vmcnt(0)
	s_add_u32 s24, s22, 0xfffc0080
	s_addc_u32 s25, s23, -1
	s_add_i32 s64, 0, 0x10000
	s_cmp_eq_u32 s63, 12
	s_cselect_b32 s27, s15, s25
	s_cselect_b32 s26, s21, s24
	v_add_u32_e32 v0, s64, v175
	s_cselect_b32 s25, s13, s62
	s_cselect_b32 s24, s60, s61
	s_add_i32 s66, 0, 0x14000
	ds_read_b128 v[130:133], v0
	ds_read_b128 v[134:137], v0 offset:1024
	ds_read_b128 v[138:141], v0 offset:2048
	ds_read_b128 v[142:145], v0 offset:3072
	v_add_u32_e32 v0, s66, v175
	ds_read_b128 v[168:171], v0
	ds_read_b128 v[200:203], v0 offset:1024
	ds_read_b128 v[204:207], v0 offset:2048
	ds_read_b128 v[208:211], v0 offset:3072
	v_lshl_add_u64 v[146:147], s[22:23], 0, v[164:165]
	s_add_i32 m0, s50, 0xc000
	ds_read_b128 v[212:215], v177
	ds_read_b128 v[216:219], v177 offset:1024
	ds_read_b128 v[220:223], v177 offset:2048
	ds_read_b128 v[224:227], v177 offset:3072
	ds_read_b128 v[228:231], v177 offset:4096
	ds_read_b128 v[232:235], v177 offset:5120
	ds_read_b128 v[236:239], v177 offset:6144
	ds_read_b128 v[240:243], v177 offset:7168
	global_load_lds_dwordx4 v[146:147], off
	v_lshl_add_u64 v[146:147], s[22:23], 0, v[166:167]
	s_add_i32 m0, s50, 0xe000
	s_nop 0
	global_load_lds_dwordx4 v[146:147], off
	s_waitcnt vmcnt(8)
	s_waitcnt lgkmcnt(0)
	s_barrier
	s_setprio 1
	s_waitcnt lgkmcnt(0)
	v_mfma_f32_16x16x32_bf16 v[126:129], v[130:133], v[212:215], 0
	v_mfma_f32_16x16x32_bf16 v[122:125], v[138:141], v[212:215], 0
	v_mfma_f32_16x16x32_bf16 v[114:117], v[130:133], v[220:223], 0
	v_mfma_f32_16x16x32_bf16 v[106:109], v[138:141], v[220:223], 0
	v_mfma_f32_16x16x32_bf16 v[94:97], v[130:133], v[228:231], 0
	v_mfma_f32_16x16x32_bf16 v[90:93], v[138:141], v[228:231], 0
	v_mfma_f32_16x16x32_bf16 v[82:85], v[130:133], v[236:239], 0
	v_mfma_f32_16x16x32_bf16 v[74:77], v[138:141], v[236:239], 0
	v_mfma_f32_16x16x32_bf16 v[126:129], v[134:137], v[216:219], v[126:129]
	v_mfma_f32_16x16x32_bf16 v[122:125], v[142:145], v[216:219], v[122:125]
	v_mfma_f32_16x16x32_bf16 v[114:117], v[134:137], v[224:227], v[114:117]
	v_mfma_f32_16x16x32_bf16 v[106:109], v[142:145], v[224:227], v[106:109]
	v_mfma_f32_16x16x32_bf16 v[94:97], v[134:137], v[232:235], v[94:97]
	v_mfma_f32_16x16x32_bf16 v[90:93], v[142:145], v[232:235], v[90:93]
	v_mfma_f32_16x16x32_bf16 v[82:85], v[134:137], v[240:243], v[82:85]
	v_mfma_f32_16x16x32_bf16 v[74:77], v[142:145], v[240:243], v[74:77]
	s_setprio 0
	s_setprio 1
	v_mfma_f32_16x16x32_bf16 v[118:121], v[168:171], v[212:215], 0
	v_mfma_f32_16x16x32_bf16 v[110:113], v[204:207], v[212:215], 0
	v_mfma_f32_16x16x32_bf16 v[102:105], v[168:171], v[220:223], 0
	v_mfma_f32_16x16x32_bf16 v[98:101], v[204:207], v[220:223], 0
	v_mfma_f32_16x16x32_bf16 v[86:89], v[168:171], v[228:231], 0
	v_mfma_f32_16x16x32_bf16 v[78:81], v[204:207], v[228:231], 0
	v_mfma_f32_16x16x32_bf16 v[70:73], v[168:171], v[236:239], 0
	v_mfma_f32_16x16x32_bf16 v[66:69], v[204:207], v[236:239], 0
	v_mfma_f32_16x16x32_bf16 v[118:121], v[200:203], v[216:219], v[118:121]
	v_mfma_f32_16x16x32_bf16 v[110:113], v[208:211], v[216:219], v[110:113]
	v_mfma_f32_16x16x32_bf16 v[102:105], v[200:203], v[224:227], v[102:105]
	v_mfma_f32_16x16x32_bf16 v[98:101], v[208:211], v[224:227], v[98:101]
	v_mfma_f32_16x16x32_bf16 v[86:89], v[200:203], v[232:235], v[86:89]
	v_mfma_f32_16x16x32_bf16 v[78:81], v[208:211], v[232:235], v[78:81]
	v_mfma_f32_16x16x32_bf16 v[70:73], v[200:203], v[240:243], v[70:73]
	v_mfma_f32_16x16x32_bf16 v[66:69], v[208:211], v[240:243], v[66:69]
	s_setprio 0
	s_barrier
	s_add_i32 s64, s64, s30
	v_lshl_add_u64 v[146:147], s[24:25], 0, v[158:159]
	s_mov_b32 m0, s64
	ds_read_b128 v[212:215], v177 offset:16384
	ds_read_b128 v[216:219], v177 offset:17408
	ds_read_b128 v[220:223], v177 offset:18432
	ds_read_b128 v[224:227], v177 offset:19456
	ds_read_b128 v[228:231], v177 offset:20480
	ds_read_b128 v[232:235], v177 offset:21504
	ds_read_b128 v[236:239], v177 offset:22528
	ds_read_b128 v[240:243], v177 offset:23552
	global_load_lds_dwordx4 v[146:147], off
	s_add_i32 m0, s64, 0x2000
	s_add_u32 s64, s24, 0x40000
	v_lshl_add_u64 v[148:149], s[24:25], 0, v[154:155]
	s_addc_u32 s65, s25, 0
	s_add_i32 s66, s66, s30
	global_load_lds_dwordx4 v[148:149], off
	v_lshl_add_u64 v[172:173], s[64:65], 0, v[158:159]
	s_mov_b32 m0, s66
	v_lshl_add_u64 v[180:181], s[26:27], 0, v[156:157]
	global_load_lds_dwordx4 v[172:173], off
	v_lshl_add_u64 v[172:173], s[64:65], 0, v[154:155]
	s_add_i32 m0, s66, 0x2000
	s_nop 0
	global_load_lds_dwordx4 v[172:173], off
	v_lshl_add_u64 v[172:173], s[26:27], 0, v[160:161]
	s_mov_b32 m0, s50
	s_nop 0
	global_load_lds_dwordx4 v[172:173], off
	s_mov_b32 m0, s51
	s_nop 0
	global_load_lds_dwordx4 v[180:181], off
	s_waitcnt vmcnt(8)
	s_waitcnt lgkmcnt(0)
	s_barrier
; #define PG8_STAGE(bufoff, gbase, voff) do { _Pragma("unroll") for (int _i = 0; _i < 2; ++_i) \
;         __builtin_amdgcn_global_load_lds((const unsigned*)((const char*)(gbase) + (voff)[_i]), (PG8_LAS unsigned*)(lds + (bufoff) + ldsw + _i * 8192), 16, 0, 0); } while (0)
; #define PG8_LDA(dst, b, h) do { _Pragma("unroll") for (int m = 0; m < 4; ++m) _Pragma("unroll") for (int k = 0; k < 2; ++k) dst[m][k] = *(const PG8_LAS bf16x8*)(lds + PG8_SA(b, h) + aoff + m * 2048 + k * 1024); } while (0)
; #define PG8_LDB(dst, b, h) do { _Pragma("unroll") for (int n = 0; n < 2; ++n) _Pragma("unroll") for (int k = 0; k < 2; ++k) dst[n][k] = *(const PG8_LAS bf16x8*)(lds + PG8_SB(b, h) + boff + n * 2048 + k * 1024); } while (0)
; #define PG8_MMA(ai, bj, At, Bt) do { __builtin_amdgcn_s_setprio(1); _Pragma("unroll") for (int m = 0; m < 4; ++m) _Pragma("unroll") for (int n = 0; n < 2; ++n) _Pragma("unroll") for (int k = 0; k < 2; ++k) \
;         acc[ai][bj][m][n] = __builtin_amdgcn_mfma_f32_16x16x32_bf16(Bt[n][k], At[m][k], acc[ai][bj][m][n], 0, 0, 0); __builtin_amdgcn_s_setprio(0); } while (0)
; #define PG8_WAIT_V(n) asm volatile("s_waitcnt vmcnt(" #n ")" ::: "memory")
; #define PG8_WAIT_L(n) asm volatile("s_waitcnt lgkmcnt(" #n ")" ::: "memory")
; #define PG8_BAR __builtin_amdgcn_s_barrier()
; #define PG8_SCHED __builtin_amdgcn_sched_barrier(0)
; template <class Epi, class Sched, bool ALIGN_EPI = false, bool SP2 = false>
; __device__ __forceinline__ void gemm_phase(PG8_LAS unsigned char* lds, const Gemm g, const Sched& S, const Epi& E) {
;     ...
;             PG8_WAIT_V(8); PG8_WAIT_L(0); PG8_BAR; PG8_MMA(1, 0, At, B0); PG8_MMA(1, 1, At, B1); PG8_BAR; PG8_SCHED;
;             PG8_LDB(B0, 1, 0); PG8_LDB(B1, 1, 1); PG8_SCHED; PG8_LDA(At, 1, 0); PG8_STAGE(PG8_SA(0, 1), a2 + hstep, voffA);
;             PG8_WAIT_V(8); PG8_WAIT_L(0); PG8_BAR; PG8_MMA(0, 0, At, B0); PG8_MMA(0, 1, At, B1); PG8_BAR; PG8_SCHED;
;             PG8_LDA(At, 1, 1); PG8_STAGE(PG8_SB(1, 0), b3, voffB); PG8_STAGE(PG8_SB(1, 1), b3 + hstep, voffB); PG8_STAGE(PG8_SA(1, 0), a3, voffA);
	s_setprio 1
	s_waitcnt lgkmcnt(0)
	v_mfma_f32_16x16x32_bf16 v[62:65], v[130:133], v[212:215], 0
	v_mfma_f32_16x16x32_bf16 v[58:61], v[138:141], v[212:215], 0
	v_mfma_f32_16x16x32_bf16 v[50:53], v[130:133], v[220:223], 0
	v_mfma_f32_16x16x32_bf16 v[42:45], v[138:141], v[220:223], 0
	v_mfma_f32_16x16x32_bf16 v[30:33], v[130:133], v[228:231], 0
	v_mfma_f32_16x16x32_bf16 v[26:29], v[138:141], v[228:231], 0
	v_mfma_f32_16x16x32_bf16 v[18:21], v[130:133], v[236:239], 0
	v_mfma_f32_16x16x32_bf16 v[10:13], v[138:141], v[236:239], 0
	v_mfma_f32_16x16x32_bf16 v[62:65], v[134:137], v[216:219], v[62:65]
	v_mfma_f32_16x16x32_bf16 v[58:61], v[142:145], v[216:219], v[58:61]
	v_mfma_f32_16x16x32_bf16 v[50:53], v[134:137], v[224:227], v[50:53]
	v_mfma_f32_16x16x32_bf16 v[42:45], v[142:145], v[224:227], v[42:45]
	v_mfma_f32_16x16x32_bf16 v[30:33], v[134:137], v[232:235], v[30:33]
	v_mfma_f32_16x16x32_bf16 v[26:29], v[142:145], v[232:235], v[26:29]
	v_mfma_f32_16x16x32_bf16 v[18:21], v[134:137], v[240:243], v[18:21]
	v_mfma_f32_16x16x32_bf16 v[10:13], v[142:145], v[240:243], v[10:13]
	s_setprio 0
	s_setprio 1
	v_mfma_f32_16x16x32_bf16 v[54:57], v[168:171], v[212:215], 0
	v_mfma_f32_16x16x32_bf16 v[46:49], v[204:207], v[212:215], 0
	v_mfma_f32_16x16x32_bf16 v[38:41], v[168:171], v[220:223], 0
	v_mfma_f32_16x16x32_bf16 v[34:37], v[204:207], v[220:223], 0
	v_mfma_f32_16x16x32_bf16 v[22:25], v[168:171], v[228:231], 0
	v_mfma_f32_16x16x32_bf16 v[14:17], v[204:207], v[228:231], 0
	v_mfma_f32_16x16x32_bf16 v[6:9], v[168:171], v[236:239], 0
	v_mfma_f32_16x16x32_bf16 v[2:5], v[204:207], v[236:239], 0
	v_mfma_f32_16x16x32_bf16 v[54:57], v[200:203], v[216:219], v[54:57]
	v_mfma_f32_16x16x32_bf16 v[46:49], v[208:211], v[216:219], v[46:49]
	v_mfma_f32_16x16x32_bf16 v[38:41], v[200:203], v[224:227], v[38:41]
	v_mfma_f32_16x16x32_bf16 v[34:37], v[208:211], v[224:227], v[34:37]
	v_mfma_f32_16x16x32_bf16 v[22:25], v[200:203], v[232:235], v[22:25]
	v_mfma_f32_16x16x32_bf16 v[14:17], v[208:211], v[232:235], v[14:17]
	v_mfma_f32_16x16x32_bf16 v[6:9], v[200:203], v[240:243], v[6:9]
	v_mfma_f32_16x16x32_bf16 v[2:5], v[208:211], v[240:243], v[2:5]
	s_setprio 0
	s_barrier
	s_add_i32 s64, 0, 0x18000
	v_add_u32_e32 v0, s64, v175
	s_add_i32 s65, 0, 0x1c000
	ds_read_b128 v[130:133], v0
	ds_read_b128 v[134:137], v0 offset:1024
	ds_read_b128 v[138:141], v0 offset:2048
	ds_read_b128 v[142:145], v0 offset:3072
	v_add_u32_e32 v0, s65, v175
	ds_read_b128 v[168:171], v0
	ds_read_b128 v[200:203], v0 offset:1024
	ds_read_b128 v[204:207], v0 offset:2048
	ds_read_b128 v[208:211], v0 offset:3072
	s_add_u32 s26, s26, 0x40000
	s_addc_u32 s27, s27, 0
	s_mov_b32 m0, s52
	v_lshl_add_u64 v[244:245], s[26:27], 0, v[160:161]
	ds_read_b128 v[212:215], v177 offset:32768
	ds_read_b128 v[216:219], v177 offset:33792
	ds_read_b128 v[220:223], v177 offset:34816
	ds_read_b128 v[224:227], v177 offset:35840
	ds_read_b128 v[228:231], v177 offset:36864
	ds_read_b128 v[232:235], v177 offset:37888
	ds_read_b128 v[236:239], v177 offset:38912
	ds_read_b128 v[240:243], v177 offset:39936
	global_load_lds_dwordx4 v[244:245], off
	v_lshl_add_u64 v[244:245], s[26:27], 0, v[156:157]
	s_mov_b32 m0, s53
	s_nop 0
	global_load_lds_dwordx4 v[244:245], off
	s_waitcnt vmcnt(8)
	s_waitcnt lgkmcnt(0)
	s_barrier
	s_setprio 1
	s_waitcnt lgkmcnt(0)
	v_mfma_f32_16x16x32_bf16 v[126:129], v[130:133], v[212:215], v[126:129]
	v_mfma_f32_16x16x32_bf16 v[122:125], v[138:141], v[212:215], v[122:125]
	v_mfma_f32_16x16x32_bf16 v[114:117], v[130:133], v[220:223], v[114:117]
	v_mfma_f32_16x16x32_bf16 v[106:109], v[138:141], v[220:223], v[106:109]
	v_mfma_f32_16x16x32_bf16 v[94:97], v[130:133], v[228:231], v[94:97]
	v_mfma_f32_16x16x32_bf16 v[90:93], v[138:141], v[228:231], v[90:93]
	v_mfma_f32_16x16x32_bf16 v[82:85], v[130:133], v[236:239], v[82:85]
	v_mfma_f32_16x16x32_bf16 v[74:77], v[138:141], v[236:239], v[74:77]
	v_mfma_f32_16x16x32_bf16 v[126:129], v[134:137], v[216:219], v[126:129]
	v_mfma_f32_16x16x32_bf16 v[122:125], v[142:145], v[216:219], v[122:125]
	v_mfma_f32_16x16x32_bf16 v[114:117], v[134:137], v[224:227], v[114:117]
	v_mfma_f32_16x16x32_bf16 v[106:109], v[142:145], v[224:227], v[106:109]
	v_mfma_f32_16x16x32_bf16 v[94:97], v[134:137], v[232:235], v[94:97]
	v_mfma_f32_16x16x32_bf16 v[90:93], v[142:145], v[232:235], v[90:93]
	v_mfma_f32_16x16x32_bf16 v[82:85], v[134:137], v[240:243], v[82:85]
	v_mfma_f32_16x16x32_bf16 v[74:77], v[142:145], v[240:243], v[74:77]
	s_setprio 0
	s_setprio 1
	v_mfma_f32_16x16x32_bf16 v[118:121], v[168:171], v[212:215], v[118:121]
	v_mfma_f32_16x16x32_bf16 v[110:113], v[204:207], v[212:215], v[110:113]
	v_mfma_f32_16x16x32_bf16 v[102:105], v[168:171], v[220:223], v[102:105]
	v_mfma_f32_16x16x32_bf16 v[98:101], v[204:207], v[220:223], v[98:101]
	v_mfma_f32_16x16x32_bf16 v[86:89], v[168:171], v[228:231], v[86:89]
	v_mfma_f32_16x16x32_bf16 v[78:81], v[204:207], v[228:231], v[78:81]
	v_mfma_f32_16x16x32_bf16 v[70:73], v[168:171], v[236:239], v[70:73]
	v_mfma_f32_16x16x32_bf16 v[66:69], v[204:207], v[236:239], v[66:69]
	v_mfma_f32_16x16x32_bf16 v[118:121], v[200:203], v[216:219], v[118:121]
	v_mfma_f32_16x16x32_bf16 v[110:113], v[208:211], v[216:219], v[110:113]
	v_mfma_f32_16x16x32_bf16 v[102:105], v[200:203], v[224:227], v[102:105]
	v_mfma_f32_16x16x32_bf16 v[98:101], v[208:211], v[224:227], v[98:101]
	v_mfma_f32_16x16x32_bf16 v[86:89], v[200:203], v[232:235], v[86:89]
	v_mfma_f32_16x16x32_bf16 v[78:81], v[208:211], v[232:235], v[78:81]
	v_mfma_f32_16x16x32_bf16 v[70:73], v[200:203], v[240:243], v[70:73]
	v_mfma_f32_16x16x32_bf16 v[66:69], v[208:211], v[240:243], v[66:69]
	s_setprio 0
	s_barrier
; #define PG8_STAGE(bufoff, gbase, voff) do { _Pragma("unroll") for (int _i = 0; _i < 2; ++_i) \
;         __builtin_amdgcn_global_load_lds((const unsigned*)((const char*)(gbase) + (voff)[_i]), (PG8_LAS unsigned*)(lds + (bufoff) + ldsw + _i * 8192), 16, 0, 0); } while (0)
; #define PG8_LDA(dst, b, h) do { _Pragma("unroll") for (int m = 0; m < 4; ++m) _Pragma("unroll") for (int k = 0; k < 2; ++k) dst[m][k] = *(const PG8_LAS bf16x8*)(lds + PG8_SA(b, h) + aoff + m * 2048 + k * 1024); } while (0)
; #define PG8_MMA(ai, bj, At, Bt) do { __builtin_amdgcn_s_setprio(1); _Pragma("unroll") for (int m = 0; m < 4; ++m) _Pragma("unroll") for (int n = 0; n < 2; ++n) _Pragma("unroll") for (int k = 0; k < 2; ++k) \
;         acc[ai][bj][m][n] = __builtin_amdgcn_mfma_f32_16x16x32_bf16(Bt[n][k], At[m][k], acc[ai][bj][m][n], 0, 0, 0); __builtin_amdgcn_s_setprio(0); } while (0)
; #define PG8_WAIT_V(n) asm volatile("s_waitcnt vmcnt(" #n ")" ::: "memory")
; #define PG8_WAIT_L(n) asm volatile("s_waitcnt lgkmcnt(" #n ")" ::: "memory")
; #define PG8_BAR __builtin_amdgcn_s_barrier()
; #define PG8_SCHED __builtin_amdgcn_sched_barrier(0)
; template <class Epi, class Sched, bool ALIGN_EPI = false, bool SP2 = false>
; __device__ __forceinline__ void gemm_phase(PG8_LAS unsigned char* lds, const Gemm g, const Sched& S, const Epi& E) {
;     ...
;         for (int t = 0; t < nt; t += 2) {
;             const bool last = (t == nt - 2);
;             const char* a1 = cA + (size_t)(t + 1) * kstep;
;             const char* a2 = last ? nA : cA + (size_t)(t + 2) * kstep; const char* b2 = last ? nB : cB + (size_t)(t + 2) * kstep;
;             const char* a3 = a2 + kstep; const char* b3 = b2 + kstep;
;     ...
;             PG8_LDA(At, 1, 1); PG8_STAGE(PG8_SB(1, 0), b3, voffB); PG8_STAGE(PG8_SB(1, 1), b3 + hstep, voffB); PG8_STAGE(PG8_SA(1, 0), a3, voffA);
;             PG8_WAIT_V(8); PG8_WAIT_L(0); PG8_BAR; PG8_MMA(1, 0, At, B0); PG8_MMA(1, 1, At, B1); PG8_BAR; PG8_SCHED;
	s_add_i32 s26, s64, s30
	v_lshl_add_u64 v[146:147], v[146:147], 0, s[38:39]
	s_mov_b32 m0, s26
	ds_read_b128 v[212:215], v177 offset:49152
	ds_read_b128 v[216:219], v177 offset:50176
	ds_read_b128 v[220:223], v177 offset:51200
	ds_read_b128 v[224:227], v177 offset:52224
	ds_read_b128 v[228:231], v177 offset:53248
	ds_read_b128 v[232:235], v177 offset:54272
	ds_read_b128 v[236:239], v177 offset:55296
	ds_read_b128 v[240:243], v177 offset:56320
	global_load_lds_dwordx4 v[146:147], off
	s_add_i32 m0, s26, 0x2000
	s_add_u32 s24, s24, 0x40080
	v_lshl_add_u64 v[146:147], v[148:149], 0, s[38:39]
	s_addc_u32 s25, s25, 0
	s_add_i32 s26, s65, s30
	global_load_lds_dwordx4 v[146:147], off
	v_lshl_add_u64 v[146:147], s[24:25], 0, v[158:159]
	s_mov_b32 m0, s26
	s_nop 0
	global_load_lds_dwordx4 v[146:147], off
	v_lshl_add_u64 v[146:147], s[24:25], 0, v[154:155]
	s_add_i32 m0, s26, 0x2000
	s_nop 0
	global_load_lds_dwordx4 v[146:147], off
	v_lshl_add_u64 v[146:147], v[172:173], 0, s[38:39]
	s_mov_b32 m0, s55
	s_nop 0
	global_load_lds_dwordx4 v[146:147], off
	v_lshl_add_u64 v[146:147], v[180:181], 0, s[38:39]
	s_mov_b32 m0, s56
	s_nop 0
	global_load_lds_dwordx4 v[146:147], off
	s_waitcnt vmcnt(8)
	s_waitcnt lgkmcnt(0)
	s_barrier
	s_setprio 1
	s_waitcnt lgkmcnt(0)
	v_mfma_f32_16x16x32_bf16 v[62:65], v[130:133], v[212:215], v[62:65]
	v_mfma_f32_16x16x32_bf16 v[58:61], v[138:141], v[212:215], v[58:61]
	v_mfma_f32_16x16x32_bf16 v[50:53], v[130:133], v[220:223], v[50:53]
	v_mfma_f32_16x16x32_bf16 v[42:45], v[138:141], v[220:223], v[42:45]
	v_mfma_f32_16x16x32_bf16 v[30:33], v[130:133], v[228:231], v[30:33]
	v_mfma_f32_16x16x32_bf16 v[26:29], v[138:141], v[228:231], v[26:29]
	v_mfma_f32_16x16x32_bf16 v[18:21], v[130:133], v[236:239], v[18:21]
	v_mfma_f32_16x16x32_bf16 v[10:13], v[138:141], v[236:239], v[10:13]
	v_mfma_f32_16x16x32_bf16 v[62:65], v[134:137], v[216:219], v[62:65]
	v_mfma_f32_16x16x32_bf16 v[58:61], v[142:145], v[216:219], v[58:61]
	v_mfma_f32_16x16x32_bf16 v[50:53], v[134:137], v[224:227], v[50:53]
	v_mfma_f32_16x16x32_bf16 v[42:45], v[142:145], v[224:227], v[42:45]
	v_mfma_f32_16x16x32_bf16 v[30:33], v[134:137], v[232:235], v[30:33]
	v_mfma_f32_16x16x32_bf16 v[26:29], v[142:145], v[232:235], v[26:29]
	v_mfma_f32_16x16x32_bf16 v[18:21], v[134:137], v[240:243], v[18:21]
	v_mfma_f32_16x16x32_bf16 v[10:13], v[142:145], v[240:243], v[10:13]
	s_setprio 0
	s_setprio 1
	v_mfma_f32_16x16x32_bf16 v[54:57], v[168:171], v[212:215], v[54:57]
	v_mfma_f32_16x16x32_bf16 v[46:49], v[204:207], v[212:215], v[46:49]
	v_mfma_f32_16x16x32_bf16 v[38:41], v[168:171], v[220:223], v[38:41]
	v_mfma_f32_16x16x32_bf16 v[34:37], v[204:207], v[220:223], v[34:37]
	v_mfma_f32_16x16x32_bf16 v[22:25], v[168:171], v[228:231], v[22:25]
	v_mfma_f32_16x16x32_bf16 v[14:17], v[204:207], v[228:231], v[14:17]
	v_mfma_f32_16x16x32_bf16 v[6:9], v[168:171], v[236:239], v[6:9]
	v_mfma_f32_16x16x32_bf16 v[2:5], v[204:207], v[236:239], v[2:5]
	v_mfma_f32_16x16x32_bf16 v[54:57], v[200:203], v[216:219], v[54:57]
	v_mfma_f32_16x16x32_bf16 v[46:49], v[208:211], v[216:219], v[46:49]
	v_mfma_f32_16x16x32_bf16 v[38:41], v[200:203], v[224:227], v[38:41]
	v_mfma_f32_16x16x32_bf16 v[34:37], v[208:211], v[224:227], v[34:37]
	v_mfma_f32_16x16x32_bf16 v[22:25], v[200:203], v[232:235], v[22:25]
	v_mfma_f32_16x16x32_bf16 v[14:17], v[208:211], v[232:235], v[14:17]
	v_mfma_f32_16x16x32_bf16 v[6:9], v[200:203], v[240:243], v[6:9]
	v_mfma_f32_16x16x32_bf16 v[2:5], v[208:211], v[240:243], v[2:5]
	s_setprio 0
	s_barrier
	s_add_i32 s63, s63, 2
	s_add_u32 s22, s22, 0x100
	s_addc_u32 s23, s23, 0
	s_add_u32 s61, s61, 0x100
	s_addc_u32 s62, s62, 0

; #define PG8_STAGE(bufoff, gbase, voff) do { _Pragma("unroll") for (int _i = 0; _i < 2; ++_i) \
;         __builtin_amdgcn_global_load_lds((const unsigned*)((const char*)(gbase) + (voff)[_i]), (PG8_LAS unsigned*)(lds + (bufoff) + ldsw + _i * 8192), 16, 0, 0); } while (0)
; #define PG8_LDA(dst, b, h) do { _Pragma("unroll") for (int m = 0; m < 4; ++m) _Pragma("unroll") for (int k = 0; k < 2; ++k) dst[m][k] = *(const PG8_LAS bf16x8*)(lds + PG8_SA(b, h) + aoff + m * 2048 + k * 1024); } while (0)
; #define PG8_LDB(dst, b, h) do { _Pragma("unroll") for (int n = 0; n < 2; ++n) _Pragma("unroll") for (int k = 0; k < 2; ++k) dst[n][k] = *(const PG8_LAS bf16x8*)(lds + PG8_SB(b, h) + boff + n * 2048 + k * 1024); } while (0)
; #define PG8_MMA(ai, bj, At, Bt) do { __builtin_amdgcn_s_setprio(1); _Pragma("unroll") for (int m = 0; m < 4; ++m) _Pragma("unroll") for (int n = 0; n < 2; ++n) _Pragma("unroll") for (int k = 0; k < 2; ++k) \
;         acc[ai][bj][m][n] = __builtin_amdgcn_mfma_f32_16x16x32_bf16(Bt[n][k], At[m][k], acc[ai][bj][m][n], 0, 0, 0); __builtin_amdgcn_s_setprio(0); } while (0)
; #define PG8_BAR __builtin_amdgcn_s_barrier()
; template <class Epi, class Sched, bool ALIGN_EPI = false, bool SP2 = false>
; __device__ __forceinline__ void gemm_phase(PG8_LAS unsigned char* lds, const Gemm g, const Sched& S, const Epi& E) {
;     ...
;         const bool has_next = S.next(ui + 1, nxt);
;         const char* nA = has_next ? (const char*)g.A + (size_t)nxt.pm * tstep : cA; const char* nB = has_next ? (const char*)g.Bt + (size_t)nxt.pn * tstep : cB;
;         for (int t = 0; t < nt; t += 2) {
;             const bool last = (t == nt - 2);
;             const char* a1 = cA + (size_t)(t + 1) * kstep;
;             const char* a2 = last ? nA : cA + (size_t)(t + 2) * kstep; const char* b2 = last ? nB : cB + (size_t)(t + 2) * kstep;
;             const char* a3 = a2 + kstep; const char* b3 = b2 + kstep;
;             if (last && has_next) S.a_ready(nxt);
;             if constexpr (SP2) {
;             PG8_LDB(B0, 0, 0); PG8_LDB(B1, 0, 1); PG8_SCHED; PG8_LDA(At, 0, 0); PG8_STAGE(PG8_SA(1, 1), a1 + hstep, voffA);
;             PG8_WAIT_V(8); PG8_WAIT_L(0); PG8_BAR; PG8_MMA(0, 0, At, B0); PG8_MMA(0, 1, At, B1); PG8_BAR; PG8_SCHED;
;             PG8_LDA(At, 0, 1); PG8_STAGE(PG8_SB(0, 0), b2, voffB); PG8_STAGE(PG8_SB(0, 1), b2 + hstep, voffB); PG8_STAGE(PG8_SA(0, 0), a2, voffA);
.LBB0_1089:
	s_ashr_i32 s11, s10, 31
	s_lshl_b64 s[12:13], s[10:11], 19
	s_add_u32 s12, s90, s12
	s_addc_u32 s13, s91, s13
	s_and_b64 s[14:15], s[4:5], exec
	s_cselect_b32 s11, s13, s17
	s_cselect_b32 s45, s12, s16
	s_ashr_i32 s9, s8, 31
	s_lshl_b64 s[14:15], s[8:9], 19
	s_add_u32 s14, s22, s14
	s_addc_u32 s15, s23, s15
	s_and_b64 s[20:21], s[4:5], exec
	s_cselect_b32 s9, s15, s19
	s_cselect_b32 s46, s14, s18
	s_add_u32 s16, s16, 0x40080
	s_addc_u32 s17, s17, 0
	s_add_u32 s47, s18, 0x100
	s_addc_u32 s48, s19, 0
	s_mov_b32 s49, -2
	s_add_u32 s18, s16, 0xfffc0080
	s_addc_u32 s19, s17, -1
	s_add_i32 s50, 0, 0x10000
	s_cmp_eq_u32 s49, 12
	s_cselect_b32 s21, s11, s19
	s_cselect_b32 s20, s45, s18
	v_add_u32_e32 v148, s50, v167
	s_cselect_b32 s19, s9, s48
	s_cselect_b32 s18, s46, s47
	s_add_i32 s52, 0, 0x14000
	ds_read_b128 v[140:143], v148
	ds_read_b128 v[144:147], v148 offset:1024
	ds_read_b128 v[154:157], v148 offset:2048
	ds_read_b128 v[158:161], v148 offset:3072
	v_add_u32_e32 v148, s52, v167
	ds_read_b128 v[162:165], v148
	ds_read_b128 v[170:173], v148 offset:1024
	ds_read_b128 v[174:177], v148 offset:2048
	ds_read_b128 v[178:181], v148 offset:3072
	v_lshl_add_u64 v[148:149], s[16:17], 0, v[136:137]
	s_add_i32 m0, s25, 0xc000
	ds_read_b128 v[200:203], v169
	ds_read_b128 v[204:207], v169 offset:1024
	ds_read_b128 v[208:211], v169 offset:2048
	ds_read_b128 v[212:215], v169 offset:3072
	ds_read_b128 v[216:219], v169 offset:4096
	ds_read_b128 v[220:223], v169 offset:5120
	ds_read_b128 v[224:227], v169 offset:6144
	ds_read_b128 v[228:231], v169 offset:7168
	global_load_lds_dwordx4 v[148:149], off
	v_lshl_add_u64 v[148:149], s[16:17], 0, v[138:139]
	s_add_i32 m0, s25, 0xe000
	s_nop 0
	global_load_lds_dwordx4 v[148:149], off
	s_waitcnt vmcnt(8)
	s_waitcnt lgkmcnt(0)
	s_barrier
	s_setprio 1
	s_waitcnt lgkmcnt(0)
	v_mfma_f32_16x16x32_bf16 v[126:129], v[140:143], v[200:203], 0
	v_mfma_f32_16x16x32_bf16 v[122:125], v[154:157], v[200:203], 0
	v_mfma_f32_16x16x32_bf16 v[118:121], v[140:143], v[208:211], 0
	v_mfma_f32_16x16x32_bf16 v[114:117], v[154:157], v[208:211], 0
	v_mfma_f32_16x16x32_bf16 v[110:113], v[140:143], v[216:219], 0
	v_mfma_f32_16x16x32_bf16 v[106:109], v[154:157], v[216:219], 0
	v_mfma_f32_16x16x32_bf16 v[102:105], v[140:143], v[224:227], 0
	v_mfma_f32_16x16x32_bf16 v[98:101], v[154:157], v[224:227], 0
	v_mfma_f32_16x16x32_bf16 v[126:129], v[144:147], v[204:207], v[126:129]
	v_mfma_f32_16x16x32_bf16 v[122:125], v[158:161], v[204:207], v[122:125]
	v_mfma_f32_16x16x32_bf16 v[118:121], v[144:147], v[212:215], v[118:121]
	v_mfma_f32_16x16x32_bf16 v[114:117], v[158:161], v[212:215], v[114:117]
	v_mfma_f32_16x16x32_bf16 v[110:113], v[144:147], v[220:223], v[110:113]
	v_mfma_f32_16x16x32_bf16 v[106:109], v[158:161], v[220:223], v[106:109]
	v_mfma_f32_16x16x32_bf16 v[102:105], v[144:147], v[228:231], v[102:105]
	v_mfma_f32_16x16x32_bf16 v[98:101], v[158:161], v[228:231], v[98:101]
	s_setprio 0
	s_setprio 1
	v_mfma_f32_16x16x32_bf16 v[62:65], v[162:165], v[200:203], 0
	v_mfma_f32_16x16x32_bf16 v[58:61], v[174:177], v[200:203], 0
	v_mfma_f32_16x16x32_bf16 v[54:57], v[162:165], v[208:211], 0
	v_mfma_f32_16x16x32_bf16 v[50:53], v[174:177], v[208:211], 0
	v_mfma_f32_16x16x32_bf16 v[46:49], v[162:165], v[216:219], 0
	v_mfma_f32_16x16x32_bf16 v[42:45], v[174:177], v[216:219], 0
	v_mfma_f32_16x16x32_bf16 v[38:41], v[162:165], v[224:227], 0
	v_mfma_f32_16x16x32_bf16 v[34:37], v[174:177], v[224:227], 0
	v_mfma_f32_16x16x32_bf16 v[62:65], v[170:173], v[204:207], v[62:65]
	v_mfma_f32_16x16x32_bf16 v[58:61], v[178:181], v[204:207], v[58:61]
	v_mfma_f32_16x16x32_bf16 v[54:57], v[170:173], v[212:215], v[54:57]
	v_mfma_f32_16x16x32_bf16 v[50:53], v[178:181], v[212:215], v[50:53]
	v_mfma_f32_16x16x32_bf16 v[46:49], v[170:173], v[220:223], v[46:49]
	v_mfma_f32_16x16x32_bf16 v[42:45], v[178:181], v[220:223], v[42:45]
	v_mfma_f32_16x16x32_bf16 v[38:41], v[170:173], v[228:231], v[38:41]
	v_mfma_f32_16x16x32_bf16 v[34:37], v[178:181], v[228:231], v[34:37]
	s_setprio 0
	s_barrier
	s_add_i32 s50, s50, s24
	v_lshl_add_u64 v[148:149], s[18:19], 0, v[0:1]
	s_mov_b32 m0, s50
	ds_read_b128 v[200:203], v169 offset:16384
	ds_read_b128 v[204:207], v169 offset:17408
	ds_read_b128 v[208:211], v169 offset:18432
	ds_read_b128 v[212:215], v169 offset:19456
	ds_read_b128 v[216:219], v169 offset:20480
	ds_read_b128 v[220:223], v169 offset:21504
	ds_read_b128 v[224:227], v169 offset:22528
	ds_read_b128 v[228:231], v169 offset:23552
	global_load_lds_dwordx4 v[148:149], off
	s_add_i32 m0, s50, 0x2000
	s_add_u32 s50, s18, 0x40000
	v_lshl_add_u64 v[232:233], s[18:19], 0, v[130:131]
	s_addc_u32 s51, s19, 0
	s_add_i32 s52, s52, s24
	global_load_lds_dwordx4 v[232:233], off
	v_lshl_add_u64 v[234:235], s[50:51], 0, v[0:1]
	s_mov_b32 m0, s52
	v_lshl_add_u64 v[236:237], s[20:21], 0, v[132:133]
	global_load_lds_dwordx4 v[234:235], off
	v_lshl_add_u64 v[234:235], s[50:51], 0, v[130:131]
	s_add_i32 m0, s52, 0x2000
	s_nop 0
	global_load_lds_dwordx4 v[234:235], off
	v_lshl_add_u64 v[234:235], s[20:21], 0, v[134:135]
	s_mov_b32 m0, s25
	s_nop 0
	global_load_lds_dwordx4 v[234:235], off
	s_mov_b32 m0, s26
	s_nop 0
	global_load_lds_dwordx4 v[236:237], off
	s_waitcnt vmcnt(8)
	s_waitcnt lgkmcnt(0)
	s_barrier
; #define PG8_STAGE(bufoff, gbase, voff) do { _Pragma("unroll") for (int _i = 0; _i < 2; ++_i) \
;         __builtin_amdgcn_global_load_lds((const unsigned*)((const char*)(gbase) + (voff)[_i]), (PG8_LAS unsigned*)(lds + (bufoff) + ldsw + _i * 8192), 16, 0, 0); } while (0)
; #define PG8_LDA(dst, b, h) do { _Pragma("unroll") for (int m = 0; m < 4; ++m) _Pragma("unroll") for (int k = 0; k < 2; ++k) dst[m][k] = *(const PG8_LAS bf16x8*)(lds + PG8_SA(b, h) + aoff + m * 2048 + k * 1024); } while (0)
; #define PG8_LDB(dst, b, h) do { _Pragma("unroll") for (int n = 0; n < 2; ++n) _Pragma("unroll") for (int k = 0; k < 2; ++k) dst[n][k] = *(const PG8_LAS bf16x8*)(lds + PG8_SB(b, h) + boff + n * 2048 + k * 1024); } while (0)
; #define PG8_MMA(ai, bj, At, Bt) do { __builtin_amdgcn_s_setprio(1); _Pragma("unroll") for (int m = 0; m < 4; ++m) _Pragma("unroll") for (int n = 0; n < 2; ++n) _Pragma("unroll") for (int k = 0; k < 2; ++k) \
;         acc[ai][bj][m][n] = __builtin_amdgcn_mfma_f32_16x16x32_bf16(Bt[n][k], At[m][k], acc[ai][bj][m][n], 0, 0, 0); __builtin_amdgcn_s_setprio(0); } while (0)
; #define PG8_WAIT_V(n) asm volatile("s_waitcnt vmcnt(" #n ")" ::: "memory")
; #define PG8_WAIT_L(n) asm volatile("s_waitcnt lgkmcnt(" #n ")" ::: "memory")
; #define PG8_BAR __builtin_amdgcn_s_barrier()
; #define PG8_SCHED __builtin_amdgcn_sched_barrier(0)
; template <class Epi, class Sched, bool ALIGN_EPI = false, bool SP2 = false>
; __device__ __forceinline__ void gemm_phase(PG8_LAS unsigned char* lds, const Gemm g, const Sched& S, const Epi& E) {
;     ...
;             PG8_WAIT_V(8); PG8_WAIT_L(0); PG8_BAR; PG8_MMA(1, 0, At, B0); PG8_MMA(1, 1, At, B1); PG8_BAR; PG8_SCHED;
;             PG8_LDB(B0, 1, 0); PG8_LDB(B1, 1, 1); PG8_SCHED; PG8_LDA(At, 1, 0); PG8_STAGE(PG8_SA(0, 1), a2 + hstep, voffA);
;             PG8_WAIT_V(8); PG8_WAIT_L(0); PG8_BAR; PG8_MMA(0, 0, At, B0); PG8_MMA(0, 1, At, B1); PG8_BAR; PG8_SCHED;
;             PG8_LDA(At, 1, 1); PG8_STAGE(PG8_SB(1, 0), b3, voffB); PG8_STAGE(PG8_SB(1, 1), b3 + hstep, voffB); PG8_STAGE(PG8_SA(1, 0), a3, voffA);
	s_setprio 1
	s_waitcnt lgkmcnt(0)
	v_mfma_f32_16x16x32_bf16 v[94:97], v[140:143], v[200:203], 0
	v_mfma_f32_16x16x32_bf16 v[90:93], v[154:157], v[200:203], 0
	v_mfma_f32_16x16x32_bf16 v[86:89], v[140:143], v[208:211], 0
	v_mfma_f32_16x16x32_bf16 v[82:85], v[154:157], v[208:211], 0
	v_mfma_f32_16x16x32_bf16 v[78:81], v[140:143], v[216:219], 0
	v_mfma_f32_16x16x32_bf16 v[74:77], v[154:157], v[216:219], 0
	v_mfma_f32_16x16x32_bf16 v[70:73], v[140:143], v[224:227], 0
	v_mfma_f32_16x16x32_bf16 v[66:69], v[154:157], v[224:227], 0
	v_mfma_f32_16x16x32_bf16 v[94:97], v[144:147], v[204:207], v[94:97]
	v_mfma_f32_16x16x32_bf16 v[90:93], v[158:161], v[204:207], v[90:93]
	v_mfma_f32_16x16x32_bf16 v[86:89], v[144:147], v[212:215], v[86:89]
	v_mfma_f32_16x16x32_bf16 v[82:85], v[158:161], v[212:215], v[82:85]
	v_mfma_f32_16x16x32_bf16 v[78:81], v[144:147], v[220:223], v[78:81]
	v_mfma_f32_16x16x32_bf16 v[74:77], v[158:161], v[220:223], v[74:77]
	v_mfma_f32_16x16x32_bf16 v[70:73], v[144:147], v[228:231], v[70:73]
	v_mfma_f32_16x16x32_bf16 v[66:69], v[158:161], v[228:231], v[66:69]
	s_setprio 0
	s_setprio 1
	v_mfma_f32_16x16x32_bf16 v[30:33], v[162:165], v[200:203], 0
	v_mfma_f32_16x16x32_bf16 v[26:29], v[174:177], v[200:203], 0
	v_mfma_f32_16x16x32_bf16 v[22:25], v[162:165], v[208:211], 0
	v_mfma_f32_16x16x32_bf16 v[18:21], v[174:177], v[208:211], 0
	v_mfma_f32_16x16x32_bf16 v[14:17], v[162:165], v[216:219], 0
	v_mfma_f32_16x16x32_bf16 v[10:13], v[174:177], v[216:219], 0
	v_mfma_f32_16x16x32_bf16 v[6:9], v[162:165], v[224:227], 0
	v_mfma_f32_16x16x32_bf16 v[2:5], v[174:177], v[224:227], 0
	v_mfma_f32_16x16x32_bf16 v[30:33], v[170:173], v[204:207], v[30:33]
	v_mfma_f32_16x16x32_bf16 v[26:29], v[178:181], v[204:207], v[26:29]
	v_mfma_f32_16x16x32_bf16 v[22:25], v[170:173], v[212:215], v[22:25]
	v_mfma_f32_16x16x32_bf16 v[18:21], v[178:181], v[212:215], v[18:21]
	v_mfma_f32_16x16x32_bf16 v[14:17], v[170:173], v[220:223], v[14:17]
	v_mfma_f32_16x16x32_bf16 v[10:13], v[178:181], v[220:223], v[10:13]
	v_mfma_f32_16x16x32_bf16 v[6:9], v[170:173], v[228:231], v[6:9]
	v_mfma_f32_16x16x32_bf16 v[2:5], v[178:181], v[228:231], v[2:5]
	s_setprio 0
	s_barrier
	s_add_i32 s50, 0, 0x18000
	s_add_i32 s51, 0, 0x1c000
	v_add_u32_e32 v158, s50, v167
	v_add_u32_e32 v178, s51, v167
	ds_read_b128 v[140:143], v158
	ds_read_b128 v[144:147], v158 offset:1024
	ds_read_b128 v[154:157], v158 offset:2048
	ds_read_b128 v[158:161], v158 offset:3072
	ds_read_b128 v[162:165], v178
	ds_read_b128 v[170:173], v178 offset:1024
	ds_read_b128 v[174:177], v178 offset:2048
	ds_read_b128 v[178:181], v178 offset:3072
	s_add_u32 s20, s20, 0x40000
	s_addc_u32 s21, s21, 0
	s_mov_b32 m0, s27
	v_lshl_add_u64 v[238:239], s[20:21], 0, v[134:135]
	ds_read_b128 v[200:203], v169 offset:32768
	ds_read_b128 v[204:207], v169 offset:33792
	ds_read_b128 v[208:211], v169 offset:34816
	ds_read_b128 v[212:215], v169 offset:35840
	ds_read_b128 v[216:219], v169 offset:36864
	ds_read_b128 v[220:223], v169 offset:37888
	ds_read_b128 v[224:227], v169 offset:38912
	ds_read_b128 v[228:231], v169 offset:39936
	global_load_lds_dwordx4 v[238:239], off
	v_lshl_add_u64 v[238:239], s[20:21], 0, v[132:133]
	s_mov_b32 m0, s28
	s_nop 0
	global_load_lds_dwordx4 v[238:239], off
	s_waitcnt vmcnt(8)
	s_waitcnt lgkmcnt(0)
	s_barrier
	s_setprio 1
	s_waitcnt lgkmcnt(0)
	v_mfma_f32_16x16x32_bf16 v[126:129], v[140:143], v[200:203], v[126:129]
	v_mfma_f32_16x16x32_bf16 v[122:125], v[154:157], v[200:203], v[122:125]
	v_mfma_f32_16x16x32_bf16 v[118:121], v[140:143], v[208:211], v[118:121]
	v_mfma_f32_16x16x32_bf16 v[114:117], v[154:157], v[208:211], v[114:117]
	v_mfma_f32_16x16x32_bf16 v[110:113], v[140:143], v[216:219], v[110:113]
	v_mfma_f32_16x16x32_bf16 v[106:109], v[154:157], v[216:219], v[106:109]
	v_mfma_f32_16x16x32_bf16 v[102:105], v[140:143], v[224:227], v[102:105]
	v_mfma_f32_16x16x32_bf16 v[98:101], v[154:157], v[224:227], v[98:101]
	v_mfma_f32_16x16x32_bf16 v[126:129], v[144:147], v[204:207], v[126:129]
	v_mfma_f32_16x16x32_bf16 v[122:125], v[158:161], v[204:207], v[122:125]
	v_mfma_f32_16x16x32_bf16 v[118:121], v[144:147], v[212:215], v[118:121]
	v_mfma_f32_16x16x32_bf16 v[114:117], v[158:161], v[212:215], v[114:117]
	v_mfma_f32_16x16x32_bf16 v[110:113], v[144:147], v[220:223], v[110:113]
	v_mfma_f32_16x16x32_bf16 v[106:109], v[158:161], v[220:223], v[106:109]
	v_mfma_f32_16x16x32_bf16 v[102:105], v[144:147], v[228:231], v[102:105]
	v_mfma_f32_16x16x32_bf16 v[98:101], v[158:161], v[228:231], v[98:101]
	s_setprio 0
	s_setprio 1
	v_mfma_f32_16x16x32_bf16 v[62:65], v[162:165], v[200:203], v[62:65]
	v_mfma_f32_16x16x32_bf16 v[58:61], v[174:177], v[200:203], v[58:61]
	v_mfma_f32_16x16x32_bf16 v[54:57], v[162:165], v[208:211], v[54:57]
	v_mfma_f32_16x16x32_bf16 v[50:53], v[174:177], v[208:211], v[50:53]
	v_mfma_f32_16x16x32_bf16 v[46:49], v[162:165], v[216:219], v[46:49]
	v_mfma_f32_16x16x32_bf16 v[42:45], v[174:177], v[216:219], v[42:45]
	v_mfma_f32_16x16x32_bf16 v[38:41], v[162:165], v[224:227], v[38:41]
	v_mfma_f32_16x16x32_bf16 v[34:37], v[174:177], v[224:227], v[34:37]
	v_mfma_f32_16x16x32_bf16 v[62:65], v[170:173], v[204:207], v[62:65]
	v_mfma_f32_16x16x32_bf16 v[58:61], v[178:181], v[204:207], v[58:61]
	v_mfma_f32_16x16x32_bf16 v[54:57], v[170:173], v[212:215], v[54:57]
	v_mfma_f32_16x16x32_bf16 v[50:53], v[178:181], v[212:215], v[50:53]
	v_mfma_f32_16x16x32_bf16 v[46:49], v[170:173], v[220:223], v[46:49]
	v_mfma_f32_16x16x32_bf16 v[42:45], v[178:181], v[220:223], v[42:45]
	v_mfma_f32_16x16x32_bf16 v[38:41], v[170:173], v[228:231], v[38:41]
	v_mfma_f32_16x16x32_bf16 v[34:37], v[178:181], v[228:231], v[34:37]
	s_setprio 0
	s_barrier
; #define PG8_STAGE(bufoff, gbase, voff) do { _Pragma("unroll") for (int _i = 0; _i < 2; ++_i) \
;         __builtin_amdgcn_global_load_lds((const unsigned*)((const char*)(gbase) + (voff)[_i]), (PG8_LAS unsigned*)(lds + (bufoff) + ldsw + _i * 8192), 16, 0, 0); } while (0)
; #define PG8_LDA(dst, b, h) do { _Pragma("unroll") for (int m = 0; m < 4; ++m) _Pragma("unroll") for (int k = 0; k < 2; ++k) dst[m][k] = *(const PG8_LAS bf16x8*)(lds + PG8_SA(b, h) + aoff + m * 2048 + k * 1024); } while (0)
; #define PG8_MMA(ai, bj, At, Bt) do { __builtin_amdgcn_s_setprio(1); _Pragma("unroll") for (int m = 0; m < 4; ++m) _Pragma("unroll") for (int n = 0; n < 2; ++n) _Pragma("unroll") for (int k = 0; k < 2; ++k) \
;         acc[ai][bj][m][n] = __builtin_amdgcn_mfma_f32_16x16x32_bf16(Bt[n][k], At[m][k], acc[ai][bj][m][n], 0, 0, 0); __builtin_amdgcn_s_setprio(0); } while (0)
; #define PG8_WAIT_V(n) asm volatile("s_waitcnt vmcnt(" #n ")" ::: "memory")
; #define PG8_WAIT_L(n) asm volatile("s_waitcnt lgkmcnt(" #n ")" ::: "memory")
; #define PG8_BAR __builtin_amdgcn_s_barrier()
; #define PG8_SCHED __builtin_amdgcn_sched_barrier(0)
; template <class Epi, class Sched, bool ALIGN_EPI = false, bool SP2 = false>
; __device__ __forceinline__ void gemm_phase(PG8_LAS unsigned char* lds, const Gemm g, const Sched& S, const Epi& E) {
;     ...
;         for (int t = 0; t < nt; t += 2) {
;             const bool last = (t == nt - 2);
;             const char* a1 = cA + (size_t)(t + 1) * kstep;
;             const char* a2 = last ? nA : cA + (size_t)(t + 2) * kstep; const char* b2 = last ? nB : cB + (size_t)(t + 2) * kstep;
;             const char* a3 = a2 + kstep; const char* b3 = b2 + kstep;
;     ...
;             PG8_LDA(At, 1, 1); PG8_STAGE(PG8_SB(1, 0), b3, voffB); PG8_STAGE(PG8_SB(1, 1), b3 + hstep, voffB); PG8_STAGE(PG8_SA(1, 0), a3, voffA);
;             PG8_WAIT_V(8); PG8_WAIT_L(0); PG8_BAR; PG8_MMA(1, 0, At, B0); PG8_MMA(1, 1, At, B1); PG8_BAR; PG8_SCHED;
	s_add_i32 s20, s50, s24
	v_lshl_add_u64 v[148:149], v[148:149], 0, s[38:39]
	s_mov_b32 m0, s20
	ds_read_b128 v[200:203], v169 offset:49152
	ds_read_b128 v[204:207], v169 offset:50176
	ds_read_b128 v[208:211], v169 offset:51200
	ds_read_b128 v[212:215], v169 offset:52224
	ds_read_b128 v[216:219], v169 offset:53248
	ds_read_b128 v[220:223], v169 offset:54272
	ds_read_b128 v[224:227], v169 offset:55296
	ds_read_b128 v[228:231], v169 offset:56320
	global_load_lds_dwordx4 v[148:149], off
	s_add_i32 m0, s20, 0x2000
	s_add_u32 s18, s18, 0x40080
	v_lshl_add_u64 v[148:149], v[232:233], 0, s[38:39]
	s_addc_u32 s19, s19, 0
	s_add_i32 s20, s51, s24
	global_load_lds_dwordx4 v[148:149], off
	v_lshl_add_u64 v[148:149], s[18:19], 0, v[0:1]
	s_mov_b32 m0, s20
	s_nop 0
	global_load_lds_dwordx4 v[148:149], off
	v_lshl_add_u64 v[148:149], s[18:19], 0, v[130:131]
	s_add_i32 m0, s20, 0x2000
	s_nop 0
	global_load_lds_dwordx4 v[148:149], off
	v_lshl_add_u64 v[148:149], v[234:235], 0, s[38:39]
	s_mov_b32 m0, s31
	s_nop 0
	global_load_lds_dwordx4 v[148:149], off
	v_lshl_add_u64 v[148:149], v[236:237], 0, s[38:39]
	s_mov_b32 m0, s33
	s_nop 0
	global_load_lds_dwordx4 v[148:149], off
	s_waitcnt vmcnt(8)
	s_waitcnt lgkmcnt(0)
	s_barrier
	s_setprio 1
	s_waitcnt lgkmcnt(0)
	v_mfma_f32_16x16x32_bf16 v[94:97], v[140:143], v[200:203], v[94:97]
	v_mfma_f32_16x16x32_bf16 v[90:93], v[154:157], v[200:203], v[90:93]
	v_mfma_f32_16x16x32_bf16 v[86:89], v[140:143], v[208:211], v[86:89]
	v_mfma_f32_16x16x32_bf16 v[82:85], v[154:157], v[208:211], v[82:85]
	v_mfma_f32_16x16x32_bf16 v[78:81], v[140:143], v[216:219], v[78:81]
	v_mfma_f32_16x16x32_bf16 v[74:77], v[154:157], v[216:219], v[74:77]
	v_mfma_f32_16x16x32_bf16 v[70:73], v[140:143], v[224:227], v[70:73]
	v_mfma_f32_16x16x32_bf16 v[66:69], v[154:157], v[224:227], v[66:69]
	v_mfma_f32_16x16x32_bf16 v[94:97], v[144:147], v[204:207], v[94:97]
	v_mfma_f32_16x16x32_bf16 v[90:93], v[158:161], v[204:207], v[90:93]
	v_mfma_f32_16x16x32_bf16 v[86:89], v[144:147], v[212:215], v[86:89]
	v_mfma_f32_16x16x32_bf16 v[82:85], v[158:161], v[212:215], v[82:85]
	v_mfma_f32_16x16x32_bf16 v[78:81], v[144:147], v[220:223], v[78:81]
	v_mfma_f32_16x16x32_bf16 v[74:77], v[158:161], v[220:223], v[74:77]
	v_mfma_f32_16x16x32_bf16 v[70:73], v[144:147], v[228:231], v[70:73]
	v_mfma_f32_16x16x32_bf16 v[66:69], v[158:161], v[228:231], v[66:69]
	s_setprio 0
	s_setprio 1
	v_mfma_f32_16x16x32_bf16 v[30:33], v[162:165], v[200:203], v[30:33]
	v_mfma_f32_16x16x32_bf16 v[26:29], v[174:177], v[200:203], v[26:29]
	v_mfma_f32_16x16x32_bf16 v[22:25], v[162:165], v[208:211], v[22:25]
	v_mfma_f32_16x16x32_bf16 v[18:21], v[174:177], v[208:211], v[18:21]
	v_mfma_f32_16x16x32_bf16 v[14:17], v[162:165], v[216:219], v[14:17]
	v_mfma_f32_16x16x32_bf16 v[10:13], v[174:177], v[216:219], v[10:13]
	v_mfma_f32_16x16x32_bf16 v[6:9], v[162:165], v[224:227], v[6:9]
	v_mfma_f32_16x16x32_bf16 v[2:5], v[174:177], v[224:227], v[2:5]
	v_mfma_f32_16x16x32_bf16 v[30:33], v[170:173], v[204:207], v[30:33]
	v_mfma_f32_16x16x32_bf16 v[26:29], v[178:181], v[204:207], v[26:29]
	v_mfma_f32_16x16x32_bf16 v[22:25], v[170:173], v[212:215], v[22:25]
	v_mfma_f32_16x16x32_bf16 v[18:21], v[178:181], v[212:215], v[18:21]
	v_mfma_f32_16x16x32_bf16 v[14:17], v[170:173], v[220:223], v[14:17]
	v_mfma_f32_16x16x32_bf16 v[10:13], v[178:181], v[220:223], v[10:13]
	v_mfma_f32_16x16x32_bf16 v[6:9], v[170:173], v[228:231], v[6:9]
	v_mfma_f32_16x16x32_bf16 v[2:5], v[178:181], v[228:231], v[2:5]
	s_setprio 0
	s_barrier
	s_add_i32 s49, s49, 2
	s_add_u32 s16, s16, 0x100
	s_addc_u32 s17, s17, 0
	s_add_u32 s47, s47, 0x100
	s_addc_u32 s48, s48, 0
